# union of the small edits: early P9 start + attention prefetch/bias/setprio cleanups + two-unit rstd table + K-loop loop-edge hoist
# speedup vs baseline: 1.0029x; 1.0029x over previous
.LBB0_189:
	ds_read_b128 v[156:159], v152
	ds_read_b128 v[160:163], v152 offset:1024
	ds_read_b128 v[164:167], v152 offset:2048
	ds_read_b128 v[168:171], v152 offset:3072
	ds_read_b128 v[172:175], v153
	ds_read_b128 v[176:179], v153 offset:1024
	ds_read_b128 v[180:183], v153 offset:2048
	ds_read_b128 v[184:187], v153 offset:3072
	s_add_u32 s82, s80, 0xfffc0080
	s_addc_u32 s83, s81, -1
	s_cmp_eq_u32 s96, 12
	s_cselect_b32 s85, s10, s83
	s_cselect_b32 s84, s11, s82
	s_cselect_b32 s83, s63, s95
	s_cselect_b32 s82, s65, s94
	v_lshl_add_u64 v[144:145], s[80:81], 0, v[136:137]
	s_add_i32 m0, s45, 0xc000
	ds_read_b128 v[188:191], v154
	ds_read_b128 v[192:195], v154 offset:1024
	ds_read_b128 v[200:203], v154 offset:2048
	ds_read_b128 v[204:207], v154 offset:3072
	ds_read_b128 v[208:211], v154 offset:4096
	ds_read_b128 v[212:215], v154 offset:5120
	ds_read_b128 v[216:219], v154 offset:6144
	ds_read_b128 v[224:227], v154 offset:7168
	global_load_lds_dwordx4 v[144:145], off
	v_lshl_add_u64 v[144:145], s[80:81], 0, v[138:139]
	s_add_i32 m0, s45, 0xe000
	s_nop 0
	global_load_lds_dwordx4 v[144:145], off
	s_waitcnt vmcnt(8)
	s_waitcnt lgkmcnt(0)
	s_barrier
	s_setprio 1
	s_waitcnt lgkmcnt(0)
	v_mfma_f32_16x16x32_bf16 v[124:127], v[156:159], v[188:191], v[124:127]
	v_mfma_f32_16x16x32_bf16 v[120:123], v[164:167], v[188:191], v[120:123]
	v_mfma_f32_16x16x32_bf16 v[108:111], v[156:159], v[200:203], v[108:111]
	v_mfma_f32_16x16x32_bf16 v[104:107], v[164:167], v[200:203], v[104:107]
	v_mfma_f32_16x16x32_bf16 v[92:95], v[156:159], v[208:211], v[92:95]
	v_mfma_f32_16x16x32_bf16 v[88:91], v[164:167], v[208:211], v[88:91]
	v_mfma_f32_16x16x32_bf16 v[76:79], v[156:159], v[216:219], v[76:79]
	v_mfma_f32_16x16x32_bf16 v[72:75], v[164:167], v[216:219], v[72:75]
	v_mfma_f32_16x16x32_bf16 v[124:127], v[160:163], v[192:195], v[124:127]
	v_mfma_f32_16x16x32_bf16 v[120:123], v[168:171], v[192:195], v[120:123]
	v_mfma_f32_16x16x32_bf16 v[108:111], v[160:163], v[204:207], v[108:111]
	v_mfma_f32_16x16x32_bf16 v[104:107], v[168:171], v[204:207], v[104:107]
	v_mfma_f32_16x16x32_bf16 v[92:95], v[160:163], v[212:215], v[92:95]
	v_mfma_f32_16x16x32_bf16 v[88:91], v[168:171], v[212:215], v[88:91]
	v_mfma_f32_16x16x32_bf16 v[76:79], v[160:163], v[224:227], v[76:79]
	v_mfma_f32_16x16x32_bf16 v[72:75], v[168:171], v[224:227], v[72:75]
	v_mfma_f32_16x16x32_bf16 v[116:119], v[172:175], v[188:191], v[116:119]
	v_mfma_f32_16x16x32_bf16 v[112:115], v[180:183], v[188:191], v[112:115]
	v_mfma_f32_16x16x32_bf16 v[100:103], v[172:175], v[200:203], v[100:103]
	v_mfma_f32_16x16x32_bf16 v[96:99], v[180:183], v[200:203], v[96:99]
	v_mfma_f32_16x16x32_bf16 v[84:87], v[172:175], v[208:211], v[84:87]
	v_mfma_f32_16x16x32_bf16 v[80:83], v[180:183], v[208:211], v[80:83]
	v_mfma_f32_16x16x32_bf16 v[68:71], v[172:175], v[216:219], v[68:71]
	v_mfma_f32_16x16x32_bf16 v[64:67], v[180:183], v[216:219], v[64:67]
	v_mfma_f32_16x16x32_bf16 v[116:119], v[176:179], v[192:195], v[116:119]
	v_mfma_f32_16x16x32_bf16 v[112:115], v[184:187], v[192:195], v[112:115]
	v_mfma_f32_16x16x32_bf16 v[100:103], v[176:179], v[204:207], v[100:103]
	v_mfma_f32_16x16x32_bf16 v[96:99], v[184:187], v[204:207], v[96:99]
	v_mfma_f32_16x16x32_bf16 v[84:87], v[176:179], v[212:215], v[84:87]
	v_mfma_f32_16x16x32_bf16 v[80:83], v[184:187], v[212:215], v[80:83]
	v_mfma_f32_16x16x32_bf16 v[68:71], v[176:179], v[224:227], v[68:71]
	v_mfma_f32_16x16x32_bf16 v[64:67], v[184:187], v[224:227], v[64:67]
	s_setprio 0
	s_barrier
	s_add_i32 s97, s90, s2
	v_lshl_add_u64 v[144:145], s[82:83], 0, v[132:133]
	s_mov_b32 m0, s97
	ds_read_b128 v[188:191], v154 offset:16384
	ds_read_b128 v[192:195], v154 offset:17408
	ds_read_b128 v[200:203], v154 offset:18432
	ds_read_b128 v[204:207], v154 offset:19456
	ds_read_b128 v[208:211], v154 offset:20480
	ds_read_b128 v[212:215], v154 offset:21504
	ds_read_b128 v[216:219], v154 offset:22528
	ds_read_b128 v[224:227], v154 offset:23552
	global_load_lds_dwordx4 v[144:145], off
	s_add_i32 m0, s97, 0x2000
	s_add_u32 vcc_lo, s82, 0x40000
	v_lshl_add_u64 v[196:197], s[82:83], 0, v[128:129]
	s_addc_u32 vcc_hi, s83, 0
	s_add_i32 s97, s91, s2
	global_load_lds_dwordx4 v[196:197], off
	v_lshl_add_u64 v[220:221], vcc, 0, v[132:133]
	s_mov_b32 m0, s97
	v_lshl_add_u64 v[228:229], s[84:85], 0, v[130:131]
	global_load_lds_dwordx4 v[220:221], off
	v_lshl_add_u64 v[220:221], vcc, 0, v[128:129]
	s_add_i32 m0, s97, 0x2000
	s_nop 0
	global_load_lds_dwordx4 v[220:221], off
	v_lshl_add_u64 v[220:221], s[84:85], 0, v[134:135]
	s_mov_b32 m0, s45
	s_nop 0
	global_load_lds_dwordx4 v[220:221], off
	s_mov_b32 m0, s70
	s_nop 0
	global_load_lds_dwordx4 v[228:229], off
	s_waitcnt vmcnt(8)
	s_waitcnt lgkmcnt(0)
	s_barrier
	s_setprio 1
	s_waitcnt lgkmcnt(0)
	v_mfma_f32_16x16x32_bf16 v[60:63], v[156:159], v[188:191], v[60:63]
	v_mfma_f32_16x16x32_bf16 v[56:59], v[164:167], v[188:191], v[56:59]
	v_mfma_f32_16x16x32_bf16 v[44:47], v[156:159], v[200:203], v[44:47]
	v_mfma_f32_16x16x32_bf16 v[40:43], v[164:167], v[200:203], v[40:43]
	v_mfma_f32_16x16x32_bf16 v[28:31], v[156:159], v[208:211], v[28:31]
	v_mfma_f32_16x16x32_bf16 v[24:27], v[164:167], v[208:211], v[24:27]
	v_mfma_f32_16x16x32_bf16 v[12:15], v[156:159], v[216:219], v[12:15]
	v_mfma_f32_16x16x32_bf16 v[8:11], v[164:167], v[216:219], v[8:11]
	v_mfma_f32_16x16x32_bf16 v[60:63], v[160:163], v[192:195], v[60:63]
	v_mfma_f32_16x16x32_bf16 v[56:59], v[168:171], v[192:195], v[56:59]
	v_mfma_f32_16x16x32_bf16 v[44:47], v[160:163], v[204:207], v[44:47]
	v_mfma_f32_16x16x32_bf16 v[40:43], v[168:171], v[204:207], v[40:43]
	v_mfma_f32_16x16x32_bf16 v[28:31], v[160:163], v[212:215], v[28:31]
	v_mfma_f32_16x16x32_bf16 v[24:27], v[168:171], v[212:215], v[24:27]
	v_mfma_f32_16x16x32_bf16 v[12:15], v[160:163], v[224:227], v[12:15]
	v_mfma_f32_16x16x32_bf16 v[8:11], v[168:171], v[224:227], v[8:11]
	v_mfma_f32_16x16x32_bf16 v[52:55], v[172:175], v[188:191], v[52:55]
	v_mfma_f32_16x16x32_bf16 v[48:51], v[180:183], v[188:191], v[48:51]
	v_mfma_f32_16x16x32_bf16 v[36:39], v[172:175], v[200:203], v[36:39]
	v_mfma_f32_16x16x32_bf16 v[32:35], v[180:183], v[200:203], v[32:35]
	v_mfma_f32_16x16x32_bf16 v[20:23], v[172:175], v[208:211], v[20:23]
	v_mfma_f32_16x16x32_bf16 v[16:19], v[180:183], v[208:211], v[16:19]
	v_mfma_f32_16x16x32_bf16 v[4:7], v[172:175], v[216:219], v[4:7]
	v_mfma_f32_16x16x32_bf16 v[0:3], v[180:183], v[216:219], v[0:3]
	v_mfma_f32_16x16x32_bf16 v[52:55], v[176:179], v[192:195], v[52:55]
	v_mfma_f32_16x16x32_bf16 v[48:51], v[184:187], v[192:195], v[48:51]
	v_mfma_f32_16x16x32_bf16 v[36:39], v[176:179], v[204:207], v[36:39]
	v_mfma_f32_16x16x32_bf16 v[32:35], v[184:187], v[204:207], v[32:35]
	v_mfma_f32_16x16x32_bf16 v[20:23], v[176:179], v[212:215], v[20:23]
	v_mfma_f32_16x16x32_bf16 v[16:19], v[184:187], v[212:215], v[16:19]
	v_mfma_f32_16x16x32_bf16 v[4:7], v[176:179], v[224:227], v[4:7]
	v_mfma_f32_16x16x32_bf16 v[0:3], v[184:187], v[224:227], v[0:3]
	s_setprio 0
	s_barrier
	s_add_i32 s97, 0, 0x18000
	v_add_u32_e32 v155, s97, v147
	s_add_i32 vcc_lo, 0, 0x1c000
	ds_read_b128 v[156:159], v155
	ds_read_b128 v[160:163], v155 offset:1024
	ds_read_b128 v[164:167], v155 offset:2048
	ds_read_b128 v[168:171], v155 offset:3072
	v_add_u32_e32 v155, vcc_lo, v147
	ds_read_b128 v[172:175], v155
	ds_read_b128 v[176:179], v155 offset:1024
	ds_read_b128 v[180:183], v155 offset:2048
	ds_read_b128 v[184:187], v155 offset:3072
	s_add_u32 s84, s84, 0x40000
	s_addc_u32 s85, s85, 0
	s_mov_b32 m0, s71
	v_lshl_add_u64 v[230:231], s[84:85], 0, v[134:135]
	ds_read_b128 v[188:191], v154 offset:32768
	ds_read_b128 v[192:195], v154 offset:33792
	ds_read_b128 v[200:203], v154 offset:34816
	ds_read_b128 v[204:207], v154 offset:35840
	ds_read_b128 v[208:211], v154 offset:36864
	ds_read_b128 v[212:215], v154 offset:37888
	ds_read_b128 v[216:219], v154 offset:38912
	ds_read_b128 v[224:227], v154 offset:39936
	global_load_lds_dwordx4 v[230:231], off
	v_lshl_add_u64 v[230:231], s[84:85], 0, v[130:131]
	s_mov_b32 m0, s75
	s_nop 0
	global_load_lds_dwordx4 v[230:231], off
	s_waitcnt vmcnt(8)
	s_waitcnt lgkmcnt(0)
	s_barrier
	s_setprio 1
	s_waitcnt lgkmcnt(0)
	v_mfma_f32_16x16x32_bf16 v[124:127], v[156:159], v[188:191], v[124:127]
	v_mfma_f32_16x16x32_bf16 v[120:123], v[164:167], v[188:191], v[120:123]
	v_mfma_f32_16x16x32_bf16 v[108:111], v[156:159], v[200:203], v[108:111]
	v_mfma_f32_16x16x32_bf16 v[104:107], v[164:167], v[200:203], v[104:107]
	v_mfma_f32_16x16x32_bf16 v[92:95], v[156:159], v[208:211], v[92:95]
	v_mfma_f32_16x16x32_bf16 v[88:91], v[164:167], v[208:211], v[88:91]
	v_mfma_f32_16x16x32_bf16 v[76:79], v[156:159], v[216:219], v[76:79]
	v_mfma_f32_16x16x32_bf16 v[72:75], v[164:167], v[216:219], v[72:75]
	v_mfma_f32_16x16x32_bf16 v[124:127], v[160:163], v[192:195], v[124:127]
	v_mfma_f32_16x16x32_bf16 v[120:123], v[168:171], v[192:195], v[120:123]
	v_mfma_f32_16x16x32_bf16 v[108:111], v[160:163], v[204:207], v[108:111]
	v_mfma_f32_16x16x32_bf16 v[104:107], v[168:171], v[204:207], v[104:107]
	v_mfma_f32_16x16x32_bf16 v[92:95], v[160:163], v[212:215], v[92:95]
	v_mfma_f32_16x16x32_bf16 v[88:91], v[168:171], v[212:215], v[88:91]
	v_mfma_f32_16x16x32_bf16 v[76:79], v[160:163], v[224:227], v[76:79]
	v_mfma_f32_16x16x32_bf16 v[72:75], v[168:171], v[224:227], v[72:75]
	v_mfma_f32_16x16x32_bf16 v[116:119], v[172:175], v[188:191], v[116:119]
	v_mfma_f32_16x16x32_bf16 v[112:115], v[180:183], v[188:191], v[112:115]
	v_mfma_f32_16x16x32_bf16 v[100:103], v[172:175], v[200:203], v[100:103]
	v_mfma_f32_16x16x32_bf16 v[96:99], v[180:183], v[200:203], v[96:99]
	v_mfma_f32_16x16x32_bf16 v[84:87], v[172:175], v[208:211], v[84:87]
	v_mfma_f32_16x16x32_bf16 v[80:83], v[180:183], v[208:211], v[80:83]
	v_mfma_f32_16x16x32_bf16 v[68:71], v[172:175], v[216:219], v[68:71]
	v_mfma_f32_16x16x32_bf16 v[64:67], v[180:183], v[216:219], v[64:67]
	v_mfma_f32_16x16x32_bf16 v[116:119], v[176:179], v[192:195], v[116:119]
	v_mfma_f32_16x16x32_bf16 v[112:115], v[184:187], v[192:195], v[112:115]
	v_mfma_f32_16x16x32_bf16 v[100:103], v[176:179], v[204:207], v[100:103]
	v_mfma_f32_16x16x32_bf16 v[96:99], v[184:187], v[204:207], v[96:99]
	v_mfma_f32_16x16x32_bf16 v[84:87], v[176:179], v[212:215], v[84:87]
	v_mfma_f32_16x16x32_bf16 v[80:83], v[184:187], v[212:215], v[80:83]
	v_mfma_f32_16x16x32_bf16 v[68:71], v[176:179], v[224:227], v[68:71]
	v_mfma_f32_16x16x32_bf16 v[64:67], v[184:187], v[224:227], v[64:67]
	s_setprio 0
	s_barrier
	s_add_i32 s84, s97, s2
	v_lshl_add_u64 v[144:145], v[144:145], 0, s[8:9]
	s_mov_b32 m0, s84
	ds_read_b128 v[188:191], v154 offset:49152
	ds_read_b128 v[192:195], v154 offset:50176
	ds_read_b128 v[200:203], v154 offset:51200
	ds_read_b128 v[204:207], v154 offset:52224
	ds_read_b128 v[208:211], v154 offset:53248
	ds_read_b128 v[212:215], v154 offset:54272
	ds_read_b128 v[216:219], v154 offset:55296
	ds_read_b128 v[224:227], v154 offset:56320
	global_load_lds_dwordx4 v[144:145], off
	s_add_i32 m0, s84, 0x2000
	s_add_u32 s82, s82, 0x40080
	v_lshl_add_u64 v[144:145], v[196:197], 0, s[8:9]
	s_addc_u32 s83, s83, 0
	s_add_i32 s84, vcc_lo, s2
	global_load_lds_dwordx4 v[144:145], off
	v_lshl_add_u64 v[144:145], s[82:83], 0, v[132:133]
	s_mov_b32 m0, s84
	s_nop 0
	global_load_lds_dwordx4 v[144:145], off
	v_lshl_add_u64 v[144:145], s[82:83], 0, v[128:129]
	s_add_i32 m0, s84, 0x2000
	s_nop 0
	global_load_lds_dwordx4 v[144:145], off
	v_lshl_add_u64 v[144:145], v[220:221], 0, s[8:9]
	s_mov_b32 m0, s86
	s_nop 0
	global_load_lds_dwordx4 v[144:145], off
	v_lshl_add_u64 v[144:145], v[228:229], 0, s[8:9]
	s_mov_b32 m0, s87
	s_nop 0
	global_load_lds_dwordx4 v[144:145], off
	s_add_i32 s96, s96, 2
	s_add_u32 s80, s80, 0x100
	s_addc_u32 s81, s81, 0
	s_add_u32 s94, s94, 0x100
	s_addc_u32 s95, s95, 0
	s_waitcnt vmcnt(8)
	s_waitcnt lgkmcnt(0)
	s_barrier
	s_setprio 1
	s_waitcnt lgkmcnt(0)
	v_mfma_f32_16x16x32_bf16 v[60:63], v[156:159], v[188:191], v[60:63]
	v_mfma_f32_16x16x32_bf16 v[56:59], v[164:167], v[188:191], v[56:59]
	v_mfma_f32_16x16x32_bf16 v[44:47], v[156:159], v[200:203], v[44:47]
	v_mfma_f32_16x16x32_bf16 v[40:43], v[164:167], v[200:203], v[40:43]
	v_mfma_f32_16x16x32_bf16 v[28:31], v[156:159], v[208:211], v[28:31]
	v_mfma_f32_16x16x32_bf16 v[24:27], v[164:167], v[208:211], v[24:27]
	v_mfma_f32_16x16x32_bf16 v[12:15], v[156:159], v[216:219], v[12:15]
	v_mfma_f32_16x16x32_bf16 v[8:11], v[164:167], v[216:219], v[8:11]
	v_mfma_f32_16x16x32_bf16 v[60:63], v[160:163], v[192:195], v[60:63]
	v_mfma_f32_16x16x32_bf16 v[56:59], v[168:171], v[192:195], v[56:59]
	v_mfma_f32_16x16x32_bf16 v[44:47], v[160:163], v[204:207], v[44:47]
	v_mfma_f32_16x16x32_bf16 v[40:43], v[168:171], v[204:207], v[40:43]
	v_mfma_f32_16x16x32_bf16 v[28:31], v[160:163], v[212:215], v[28:31]
	v_mfma_f32_16x16x32_bf16 v[24:27], v[168:171], v[212:215], v[24:27]
	v_mfma_f32_16x16x32_bf16 v[12:15], v[160:163], v[224:227], v[12:15]
	v_mfma_f32_16x16x32_bf16 v[8:11], v[168:171], v[224:227], v[8:11]
	v_mfma_f32_16x16x32_bf16 v[52:55], v[172:175], v[188:191], v[52:55]
	v_mfma_f32_16x16x32_bf16 v[48:51], v[180:183], v[188:191], v[48:51]
	v_mfma_f32_16x16x32_bf16 v[36:39], v[172:175], v[200:203], v[36:39]
	v_mfma_f32_16x16x32_bf16 v[32:35], v[180:183], v[200:203], v[32:35]
	v_mfma_f32_16x16x32_bf16 v[20:23], v[172:175], v[208:211], v[20:23]
	v_mfma_f32_16x16x32_bf16 v[16:19], v[180:183], v[208:211], v[16:19]
	v_mfma_f32_16x16x32_bf16 v[4:7], v[172:175], v[216:219], v[4:7]
	v_mfma_f32_16x16x32_bf16 v[0:3], v[180:183], v[216:219], v[0:3]
	v_mfma_f32_16x16x32_bf16 v[52:55], v[176:179], v[192:195], v[52:55]
	v_mfma_f32_16x16x32_bf16 v[48:51], v[184:187], v[192:195], v[48:51]
	v_mfma_f32_16x16x32_bf16 v[36:39], v[176:179], v[204:207], v[36:39]
	v_mfma_f32_16x16x32_bf16 v[32:35], v[184:187], v[204:207], v[32:35]
	v_mfma_f32_16x16x32_bf16 v[20:23], v[176:179], v[212:215], v[20:23]
	v_mfma_f32_16x16x32_bf16 v[16:19], v[184:187], v[212:215], v[16:19]
	v_mfma_f32_16x16x32_bf16 v[4:7], v[176:179], v[224:227], v[4:7]
	v_mfma_f32_16x16x32_bf16 v[0:3], v[184:187], v[224:227], v[0:3]
	s_setprio 0
	s_barrier
	s_cmp_gt_u32 s96, 13
	s_cbranch_scc0 .LBB0_189
	s_and_b64 vcc, exec, s[60:61]
	s_cbranch_vccz .LBB0_192
	s_barrier

.LBB0_340:
	ds_read_b128 v[144:147], v171
	ds_read_b128 v[148:151], v171 offset:1024
	ds_read_b128 v[152:155], v171 offset:2048
	ds_read_b128 v[156:159], v171 offset:3072
	ds_read_b128 v[160:163], v172
	ds_read_b128 v[164:167], v172 offset:1024
	ds_read_b128 v[176:179], v172 offset:2048
	ds_read_b128 v[180:183], v172 offset:3072
	s_add_u32 s56, s54, 0xfff50080
	s_addc_u32 s57, s55, -1
	s_cmp_eq_u32 s84, 40
	s_cselect_b32 s59, s7, s57
	s_cselect_b32 s58, s6, s56
	s_cselect_b32 s57, s51, s83
	s_cselect_b32 s56, s50, s82
	v_lshl_add_u64 v[196:197], s[54:55], 0, v[136:137]
	s_add_i32 m0, s17, 0xc000
	ds_read_b128 v[184:187], v173
	ds_read_b128 v[188:191], v173 offset:1024
	ds_read_b128 v[192:195], v173 offset:2048
	ds_read_b128 v[200:203], v173 offset:3072
	ds_read_b128 v[204:207], v173 offset:4096
	ds_read_b128 v[208:211], v173 offset:5120
	ds_read_b128 v[212:215], v173 offset:6144
	ds_read_b128 v[216:219], v173 offset:7168
	global_load_lds_dwordx4 v[196:197], off
	v_lshl_add_u64 v[196:197], s[54:55], 0, v[138:139]
	s_add_i32 m0, s17, 0xe000
	s_nop 0
	global_load_lds_dwordx4 v[196:197], off
	s_waitcnt vmcnt(8)
	s_waitcnt lgkmcnt(0)
	s_barrier
	s_setprio 1
	s_waitcnt lgkmcnt(0)
	v_mfma_f32_16x16x32_bf16 v[124:127], v[144:147], v[184:187], v[124:127]
	v_mfma_f32_16x16x32_bf16 v[120:123], v[152:155], v[184:187], v[120:123]
	v_mfma_f32_16x16x32_bf16 v[108:111], v[144:147], v[192:195], v[108:111]
	v_mfma_f32_16x16x32_bf16 v[104:107], v[152:155], v[192:195], v[104:107]
	v_mfma_f32_16x16x32_bf16 v[92:95], v[144:147], v[204:207], v[92:95]
	v_mfma_f32_16x16x32_bf16 v[88:91], v[152:155], v[204:207], v[88:91]
	v_mfma_f32_16x16x32_bf16 v[76:79], v[144:147], v[212:215], v[76:79]
	v_mfma_f32_16x16x32_bf16 v[72:75], v[152:155], v[212:215], v[72:75]
	v_mfma_f32_16x16x32_bf16 v[124:127], v[148:151], v[188:191], v[124:127]
	v_mfma_f32_16x16x32_bf16 v[120:123], v[156:159], v[188:191], v[120:123]
	v_mfma_f32_16x16x32_bf16 v[108:111], v[148:151], v[200:203], v[108:111]
	v_mfma_f32_16x16x32_bf16 v[104:107], v[156:159], v[200:203], v[104:107]
	v_mfma_f32_16x16x32_bf16 v[92:95], v[148:151], v[208:211], v[92:95]
	v_mfma_f32_16x16x32_bf16 v[88:91], v[156:159], v[208:211], v[88:91]
	v_mfma_f32_16x16x32_bf16 v[76:79], v[148:151], v[216:219], v[76:79]
	v_mfma_f32_16x16x32_bf16 v[72:75], v[156:159], v[216:219], v[72:75]
	v_mfma_f32_16x16x32_bf16 v[116:119], v[160:163], v[184:187], v[116:119]
	v_mfma_f32_16x16x32_bf16 v[112:115], v[176:179], v[184:187], v[112:115]
	v_mfma_f32_16x16x32_bf16 v[100:103], v[160:163], v[192:195], v[100:103]
	v_mfma_f32_16x16x32_bf16 v[96:99], v[176:179], v[192:195], v[96:99]
	v_mfma_f32_16x16x32_bf16 v[84:87], v[160:163], v[204:207], v[84:87]
	v_mfma_f32_16x16x32_bf16 v[80:83], v[176:179], v[204:207], v[80:83]
	v_mfma_f32_16x16x32_bf16 v[68:71], v[160:163], v[212:215], v[68:71]
	v_mfma_f32_16x16x32_bf16 v[64:67], v[176:179], v[212:215], v[64:67]
	v_mfma_f32_16x16x32_bf16 v[116:119], v[164:167], v[188:191], v[116:119]
	v_mfma_f32_16x16x32_bf16 v[112:115], v[180:183], v[188:191], v[112:115]
	v_mfma_f32_16x16x32_bf16 v[100:103], v[164:167], v[200:203], v[100:103]
	v_mfma_f32_16x16x32_bf16 v[96:99], v[180:183], v[200:203], v[96:99]
	v_mfma_f32_16x16x32_bf16 v[84:87], v[164:167], v[208:211], v[84:87]
	v_mfma_f32_16x16x32_bf16 v[80:83], v[180:183], v[208:211], v[80:83]
	v_mfma_f32_16x16x32_bf16 v[68:71], v[164:167], v[216:219], v[68:71]
	v_mfma_f32_16x16x32_bf16 v[64:67], v[180:183], v[216:219], v[64:67]
	s_setprio 0
	s_barrier
	s_add_i32 s85, s78, s16
	v_lshl_add_u64 v[196:197], s[56:57], 0, v[130:131]
	s_mov_b32 m0, s85
	ds_read_b128 v[184:187], v173 offset:16384
	ds_read_b128 v[188:191], v173 offset:17408
	ds_read_b128 v[192:195], v173 offset:18432
	ds_read_b128 v[200:203], v173 offset:19456
	ds_read_b128 v[204:207], v173 offset:20480
	ds_read_b128 v[208:211], v173 offset:21504
	ds_read_b128 v[212:215], v173 offset:22528
	ds_read_b128 v[216:219], v173 offset:23552
	global_load_lds_dwordx4 v[196:197], off
	s_add_i32 m0, s85, 0x2000
	s_add_u32 s86, s56, 0xb0000
	v_lshl_add_u64 v[220:221], s[56:57], 0, v[134:135]
	s_addc_u32 s87, s57, 0
	s_add_i32 s85, s79, s16
	global_load_lds_dwordx4 v[220:221], off
	v_lshl_add_u64 v[224:225], s[86:87], 0, v[130:131]
	s_mov_b32 m0, s85
	v_lshl_add_u64 v[226:227], s[58:59], 0, v[132:133]
	global_load_lds_dwordx4 v[224:225], off
	v_lshl_add_u64 v[224:225], s[86:87], 0, v[134:135]
	s_add_i32 m0, s85, 0x2000
	s_nop 0
	global_load_lds_dwordx4 v[224:225], off
	v_lshl_add_u64 v[224:225], s[58:59], 0, v[128:129]
	s_mov_b32 m0, s17
	s_nop 0
	global_load_lds_dwordx4 v[224:225], off
	s_mov_b32 m0, s39
	s_nop 0
	global_load_lds_dwordx4 v[226:227], off
	s_waitcnt vmcnt(8)
	s_waitcnt lgkmcnt(0)
	s_barrier
	s_setprio 1
	s_waitcnt lgkmcnt(0)
	v_mfma_f32_16x16x32_bf16 v[60:63], v[144:147], v[184:187], v[60:63]
	v_mfma_f32_16x16x32_bf16 v[56:59], v[152:155], v[184:187], v[56:59]
	v_mfma_f32_16x16x32_bf16 v[44:47], v[144:147], v[192:195], v[44:47]
	v_mfma_f32_16x16x32_bf16 v[40:43], v[152:155], v[192:195], v[40:43]
	v_mfma_f32_16x16x32_bf16 v[28:31], v[144:147], v[204:207], v[28:31]
	v_mfma_f32_16x16x32_bf16 v[24:27], v[152:155], v[204:207], v[24:27]
	v_mfma_f32_16x16x32_bf16 v[12:15], v[144:147], v[212:215], v[12:15]
	v_mfma_f32_16x16x32_bf16 v[8:11], v[152:155], v[212:215], v[8:11]
	v_mfma_f32_16x16x32_bf16 v[60:63], v[148:151], v[188:191], v[60:63]
	v_mfma_f32_16x16x32_bf16 v[56:59], v[156:159], v[188:191], v[56:59]
	v_mfma_f32_16x16x32_bf16 v[44:47], v[148:151], v[200:203], v[44:47]
	v_mfma_f32_16x16x32_bf16 v[40:43], v[156:159], v[200:203], v[40:43]
	v_mfma_f32_16x16x32_bf16 v[28:31], v[148:151], v[208:211], v[28:31]
	v_mfma_f32_16x16x32_bf16 v[24:27], v[156:159], v[208:211], v[24:27]
	v_mfma_f32_16x16x32_bf16 v[12:15], v[148:151], v[216:219], v[12:15]
	v_mfma_f32_16x16x32_bf16 v[8:11], v[156:159], v[216:219], v[8:11]
	v_mfma_f32_16x16x32_bf16 v[52:55], v[160:163], v[184:187], v[52:55]
	v_mfma_f32_16x16x32_bf16 v[48:51], v[176:179], v[184:187], v[48:51]
	v_mfma_f32_16x16x32_bf16 v[36:39], v[160:163], v[192:195], v[36:39]
	v_mfma_f32_16x16x32_bf16 v[32:35], v[176:179], v[192:195], v[32:35]
	v_mfma_f32_16x16x32_bf16 v[20:23], v[160:163], v[204:207], v[20:23]
	v_mfma_f32_16x16x32_bf16 v[16:19], v[176:179], v[204:207], v[16:19]
	v_mfma_f32_16x16x32_bf16 v[4:7], v[160:163], v[212:215], v[4:7]
	v_mfma_f32_16x16x32_bf16 v[0:3], v[176:179], v[212:215], v[0:3]
	v_mfma_f32_16x16x32_bf16 v[52:55], v[164:167], v[188:191], v[52:55]
	v_mfma_f32_16x16x32_bf16 v[48:51], v[180:183], v[188:191], v[48:51]
	v_mfma_f32_16x16x32_bf16 v[36:39], v[164:167], v[200:203], v[36:39]
	v_mfma_f32_16x16x32_bf16 v[32:35], v[180:183], v[200:203], v[32:35]
	v_mfma_f32_16x16x32_bf16 v[20:23], v[164:167], v[208:211], v[20:23]
	v_mfma_f32_16x16x32_bf16 v[16:19], v[180:183], v[208:211], v[16:19]
	v_mfma_f32_16x16x32_bf16 v[4:7], v[164:167], v[216:219], v[4:7]
	v_mfma_f32_16x16x32_bf16 v[0:3], v[180:183], v[216:219], v[0:3]
	s_setprio 0
	s_barrier
	s_add_i32 s85, 0, 0x18000
	s_add_i32 s86, 0, 0x1c000
	v_add_u32_e32 v156, s85, v169
	v_add_u32_e32 v175, s86, v169
	ds_read_b128 v[144:147], v156
	ds_read_b128 v[148:151], v156 offset:1024
	ds_read_b128 v[152:155], v156 offset:2048
	ds_read_b128 v[156:159], v156 offset:3072
	ds_read_b128 v[160:163], v175
	ds_read_b128 v[164:167], v175 offset:1024
	ds_read_b128 v[176:179], v175 offset:2048
	ds_read_b128 v[180:183], v175 offset:3072
	s_add_u32 s58, s58, 0xb0000
	s_addc_u32 s59, s59, 0
	s_mov_b32 m0, s45
	v_lshl_add_u64 v[228:229], s[58:59], 0, v[128:129]
	ds_read_b128 v[184:187], v173 offset:32768
	ds_read_b128 v[188:191], v173 offset:33792
	ds_read_b128 v[192:195], v173 offset:34816
	ds_read_b128 v[200:203], v173 offset:35840
	ds_read_b128 v[204:207], v173 offset:36864
	ds_read_b128 v[208:211], v173 offset:37888
	ds_read_b128 v[212:215], v173 offset:38912
	ds_read_b128 v[216:219], v173 offset:39936
	global_load_lds_dwordx4 v[228:229], off
	v_lshl_add_u64 v[228:229], s[58:59], 0, v[132:133]
	s_mov_b32 m0, s60
	s_nop 0
	global_load_lds_dwordx4 v[228:229], off
	s_waitcnt vmcnt(8)
	s_waitcnt lgkmcnt(0)
	s_barrier
	s_setprio 1
	s_waitcnt lgkmcnt(0)
	v_mfma_f32_16x16x32_bf16 v[124:127], v[144:147], v[184:187], v[124:127]
	v_mfma_f32_16x16x32_bf16 v[120:123], v[152:155], v[184:187], v[120:123]
	v_mfma_f32_16x16x32_bf16 v[108:111], v[144:147], v[192:195], v[108:111]
	v_mfma_f32_16x16x32_bf16 v[104:107], v[152:155], v[192:195], v[104:107]
	v_mfma_f32_16x16x32_bf16 v[92:95], v[144:147], v[204:207], v[92:95]
	v_mfma_f32_16x16x32_bf16 v[88:91], v[152:155], v[204:207], v[88:91]
	v_mfma_f32_16x16x32_bf16 v[76:79], v[144:147], v[212:215], v[76:79]
	v_mfma_f32_16x16x32_bf16 v[72:75], v[152:155], v[212:215], v[72:75]
	v_mfma_f32_16x16x32_bf16 v[124:127], v[148:151], v[188:191], v[124:127]
	v_mfma_f32_16x16x32_bf16 v[120:123], v[156:159], v[188:191], v[120:123]
	v_mfma_f32_16x16x32_bf16 v[108:111], v[148:151], v[200:203], v[108:111]
	v_mfma_f32_16x16x32_bf16 v[104:107], v[156:159], v[200:203], v[104:107]
	v_mfma_f32_16x16x32_bf16 v[92:95], v[148:151], v[208:211], v[92:95]
	v_mfma_f32_16x16x32_bf16 v[88:91], v[156:159], v[208:211], v[88:91]
	v_mfma_f32_16x16x32_bf16 v[76:79], v[148:151], v[216:219], v[76:79]
	v_mfma_f32_16x16x32_bf16 v[72:75], v[156:159], v[216:219], v[72:75]
	v_mfma_f32_16x16x32_bf16 v[116:119], v[160:163], v[184:187], v[116:119]
	v_mfma_f32_16x16x32_bf16 v[112:115], v[176:179], v[184:187], v[112:115]
	v_mfma_f32_16x16x32_bf16 v[100:103], v[160:163], v[192:195], v[100:103]
	v_mfma_f32_16x16x32_bf16 v[96:99], v[176:179], v[192:195], v[96:99]
	v_mfma_f32_16x16x32_bf16 v[84:87], v[160:163], v[204:207], v[84:87]
	v_mfma_f32_16x16x32_bf16 v[80:83], v[176:179], v[204:207], v[80:83]
	v_mfma_f32_16x16x32_bf16 v[68:71], v[160:163], v[212:215], v[68:71]
	v_mfma_f32_16x16x32_bf16 v[64:67], v[176:179], v[212:215], v[64:67]
	v_mfma_f32_16x16x32_bf16 v[116:119], v[164:167], v[188:191], v[116:119]
	v_mfma_f32_16x16x32_bf16 v[112:115], v[180:183], v[188:191], v[112:115]
	v_mfma_f32_16x16x32_bf16 v[100:103], v[164:167], v[200:203], v[100:103]
	v_mfma_f32_16x16x32_bf16 v[96:99], v[180:183], v[200:203], v[96:99]
	v_mfma_f32_16x16x32_bf16 v[84:87], v[164:167], v[208:211], v[84:87]
	v_mfma_f32_16x16x32_bf16 v[80:83], v[180:183], v[208:211], v[80:83]
	v_mfma_f32_16x16x32_bf16 v[68:71], v[164:167], v[216:219], v[68:71]
	v_mfma_f32_16x16x32_bf16 v[64:67], v[180:183], v[216:219], v[64:67]
	s_setprio 0
	s_barrier
	s_add_i32 s58, s85, s16
	v_lshl_add_u64 v[196:197], v[196:197], 0, s[18:19]
	s_mov_b32 m0, s58
	ds_read_b128 v[184:187], v173 offset:49152
	ds_read_b128 v[188:191], v173 offset:50176
	ds_read_b128 v[192:195], v173 offset:51200
	ds_read_b128 v[200:203], v173 offset:52224
	ds_read_b128 v[204:207], v173 offset:53248
	ds_read_b128 v[208:211], v173 offset:54272
	ds_read_b128 v[212:215], v173 offset:55296
	ds_read_b128 v[216:219], v173 offset:56320
	global_load_lds_dwordx4 v[196:197], off
	s_add_i32 m0, s58, 0x2000
	s_add_u32 s56, s56, 0xb0080
	v_lshl_add_u64 v[196:197], v[220:221], 0, s[18:19]
	s_addc_u32 s57, s57, 0
	s_add_i32 s58, s86, s16
	global_load_lds_dwordx4 v[196:197], off
	v_lshl_add_u64 v[196:197], s[56:57], 0, v[130:131]
	s_mov_b32 m0, s58
	s_nop 0
	global_load_lds_dwordx4 v[196:197], off
	v_lshl_add_u64 v[196:197], s[56:57], 0, v[134:135]
	s_add_i32 m0, s58, 0x2000
	s_nop 0
	global_load_lds_dwordx4 v[196:197], off
	v_lshl_add_u64 v[196:197], v[224:225], 0, s[18:19]
	s_mov_b32 m0, s67
	s_nop 0
	global_load_lds_dwordx4 v[196:197], off
	v_lshl_add_u64 v[196:197], v[226:227], 0, s[18:19]
	s_mov_b32 m0, s70
	s_nop 0
	global_load_lds_dwordx4 v[196:197], off
	s_add_i32 s84, s84, 2
	s_add_u32 s54, s54, 0x100
	s_addc_u32 s55, s55, 0
	s_add_u32 s82, s82, 0x100
	s_addc_u32 s83, s83, 0
	s_waitcnt vmcnt(8)
	s_waitcnt lgkmcnt(0)
	s_barrier
	s_setprio 1
	s_waitcnt lgkmcnt(0)
	v_mfma_f32_16x16x32_bf16 v[60:63], v[144:147], v[184:187], v[60:63]
	v_mfma_f32_16x16x32_bf16 v[56:59], v[152:155], v[184:187], v[56:59]
	v_mfma_f32_16x16x32_bf16 v[44:47], v[144:147], v[192:195], v[44:47]
	v_mfma_f32_16x16x32_bf16 v[40:43], v[152:155], v[192:195], v[40:43]
	v_mfma_f32_16x16x32_bf16 v[28:31], v[144:147], v[204:207], v[28:31]
	v_mfma_f32_16x16x32_bf16 v[24:27], v[152:155], v[204:207], v[24:27]
	v_mfma_f32_16x16x32_bf16 v[12:15], v[144:147], v[212:215], v[12:15]
	v_mfma_f32_16x16x32_bf16 v[8:11], v[152:155], v[212:215], v[8:11]
	v_mfma_f32_16x16x32_bf16 v[60:63], v[148:151], v[188:191], v[60:63]
	v_mfma_f32_16x16x32_bf16 v[56:59], v[156:159], v[188:191], v[56:59]
	v_mfma_f32_16x16x32_bf16 v[44:47], v[148:151], v[200:203], v[44:47]
	v_mfma_f32_16x16x32_bf16 v[40:43], v[156:159], v[200:203], v[40:43]
	v_mfma_f32_16x16x32_bf16 v[28:31], v[148:151], v[208:211], v[28:31]
	v_mfma_f32_16x16x32_bf16 v[24:27], v[156:159], v[208:211], v[24:27]
	v_mfma_f32_16x16x32_bf16 v[12:15], v[148:151], v[216:219], v[12:15]
	v_mfma_f32_16x16x32_bf16 v[8:11], v[156:159], v[216:219], v[8:11]
	v_mfma_f32_16x16x32_bf16 v[52:55], v[160:163], v[184:187], v[52:55]
	v_mfma_f32_16x16x32_bf16 v[48:51], v[176:179], v[184:187], v[48:51]
	v_mfma_f32_16x16x32_bf16 v[36:39], v[160:163], v[192:195], v[36:39]
	v_mfma_f32_16x16x32_bf16 v[32:35], v[176:179], v[192:195], v[32:35]
	v_mfma_f32_16x16x32_bf16 v[20:23], v[160:163], v[204:207], v[20:23]
	v_mfma_f32_16x16x32_bf16 v[16:19], v[176:179], v[204:207], v[16:19]
	v_mfma_f32_16x16x32_bf16 v[4:7], v[160:163], v[212:215], v[4:7]
	v_mfma_f32_16x16x32_bf16 v[0:3], v[176:179], v[212:215], v[0:3]
	v_mfma_f32_16x16x32_bf16 v[52:55], v[164:167], v[188:191], v[52:55]
	v_mfma_f32_16x16x32_bf16 v[48:51], v[180:183], v[188:191], v[48:51]
	v_mfma_f32_16x16x32_bf16 v[36:39], v[164:167], v[200:203], v[36:39]
	v_mfma_f32_16x16x32_bf16 v[32:35], v[180:183], v[200:203], v[32:35]
	v_mfma_f32_16x16x32_bf16 v[20:23], v[164:167], v[208:211], v[20:23]
	v_mfma_f32_16x16x32_bf16 v[16:19], v[180:183], v[208:211], v[16:19]
	v_mfma_f32_16x16x32_bf16 v[4:7], v[164:167], v[216:219], v[4:7]
	v_mfma_f32_16x16x32_bf16 v[0:3], v[180:183], v[216:219], v[0:3]
	s_setprio 0
	s_barrier
	s_cmp_gt_u32 s84, 41
	s_cbranch_scc0 .LBB0_340
	s_and_b64 vcc, exec, s[20:21]
	s_cbranch_vccz .LBB0_343
	s_barrier

.LBB0_476:
	v_add_u32_e32 v164, s71, v188
	ds_read_b128 v[128:131], v210
	ds_read_b128 v[132:135], v210 offset:1024
	ds_read_b128 v[136:139], v210 offset:2048
	ds_read_b128 v[140:143], v210 offset:3072
	ds_read_b128 v[144:147], v164
	ds_read_b128 v[148:151], v164 offset:1024
	ds_read_b128 v[152:155], v164 offset:2048
	ds_read_b128 v[178:181], v164 offset:3072
	s_add_u32 s6, s4, 0xfffc0080
	s_addc_u32 s7, s5, -1
	s_cmp_eq_u32 s91, 12
	s_cselect_b32 s13, s10, s7
	s_cselect_b32 s12, s11, s6
	s_cselect_b32 s7, s20, s90
	s_cselect_b32 s6, s83, s85
	v_lshl_add_u64 v[186:187], s[4:5], 0, v[174:175]
	s_add_i32 m0, s25, 0xc000
	ds_read_b128 v[182:185], v206
	ds_read_b128 v[218:221], v206 offset:1024
	ds_read_b128 v[224:227], v206 offset:2048
	ds_read_b128 v[228:231], v206 offset:3072
	ds_read_b128 v[232:235], v206 offset:4096
	ds_read_b128 v[236:239], v206 offset:5120
	ds_read_b128 v[240:243], v206 offset:6144
	ds_read_b128 v[244:247], v206 offset:7168
	global_load_lds_dwordx4 v[186:187], off
	v_lshl_add_u64 v[186:187], s[4:5], 0, v[176:177]
	s_add_i32 m0, s25, 0xe000
	s_nop 0
	global_load_lds_dwordx4 v[186:187], off
	s_waitcnt vmcnt(8)
	s_waitcnt lgkmcnt(0)
	s_barrier
	s_setprio 1
	s_waitcnt lgkmcnt(0)
	v_mfma_f32_16x16x32_bf16 v[112:115], v[128:131], v[182:185], v[112:115]
	v_mfma_f32_16x16x32_bf16 v[116:119], v[136:139], v[182:185], v[116:119]
	v_mfma_f32_16x16x32_bf16 v[80:83], v[128:131], v[224:227], v[80:83]
	v_mfma_f32_16x16x32_bf16 v[88:91], v[136:139], v[224:227], v[88:91]
	v_mfma_f32_16x16x32_bf16 v[64:67], v[128:131], v[232:235], v[64:67]
	v_mfma_f32_16x16x32_bf16 v[68:71], v[136:139], v[232:235], v[68:71]
	v_mfma_f32_16x16x32_bf16 v[48:51], v[128:131], v[240:243], v[48:51]
	v_mfma_f32_16x16x32_bf16 v[52:55], v[136:139], v[240:243], v[52:55]
	v_mfma_f32_16x16x32_bf16 v[112:115], v[132:135], v[218:221], v[112:115]
	v_mfma_f32_16x16x32_bf16 v[116:119], v[140:143], v[218:221], v[116:119]
	v_mfma_f32_16x16x32_bf16 v[80:83], v[132:135], v[228:231], v[80:83]
	v_mfma_f32_16x16x32_bf16 v[88:91], v[140:143], v[228:231], v[88:91]
	v_mfma_f32_16x16x32_bf16 v[64:67], v[132:135], v[236:239], v[64:67]
	v_mfma_f32_16x16x32_bf16 v[68:71], v[140:143], v[236:239], v[68:71]
	v_mfma_f32_16x16x32_bf16 v[48:51], v[132:135], v[244:247], v[48:51]
	v_mfma_f32_16x16x32_bf16 v[52:55], v[140:143], v[244:247], v[52:55]
	v_mfma_f32_16x16x32_bf16 v[120:123], v[144:147], v[182:185], v[120:123]
	v_mfma_f32_16x16x32_bf16 v[124:127], v[152:155], v[182:185], v[124:127]
	v_mfma_f32_16x16x32_bf16 v[96:99], v[144:147], v[224:227], v[96:99]
	v_mfma_f32_16x16x32_bf16 v[104:107], v[152:155], v[224:227], v[104:107]
	v_mfma_f32_16x16x32_bf16 v[72:75], v[144:147], v[232:235], v[72:75]
	v_mfma_f32_16x16x32_bf16 v[76:79], v[152:155], v[232:235], v[76:79]
	v_mfma_f32_16x16x32_bf16 v[56:59], v[144:147], v[240:243], v[56:59]
	v_mfma_f32_16x16x32_bf16 v[60:63], v[152:155], v[240:243], v[60:63]
	v_mfma_f32_16x16x32_bf16 v[120:123], v[148:151], v[218:221], v[120:123]
	v_mfma_f32_16x16x32_bf16 v[124:127], v[178:181], v[218:221], v[124:127]
	v_mfma_f32_16x16x32_bf16 v[96:99], v[148:151], v[228:231], v[96:99]
	v_mfma_f32_16x16x32_bf16 v[104:107], v[178:181], v[228:231], v[104:107]
	v_mfma_f32_16x16x32_bf16 v[72:75], v[148:151], v[236:239], v[72:75]
	v_mfma_f32_16x16x32_bf16 v[76:79], v[178:181], v[236:239], v[76:79]
	v_mfma_f32_16x16x32_bf16 v[56:59], v[148:151], v[244:247], v[56:59]
	v_mfma_f32_16x16x32_bf16 v[60:63], v[178:181], v[244:247], v[60:63]
	s_setprio 0
	s_barrier
	s_add_i32 s92, s70, s62
	v_lshl_add_u64 v[186:187], s[6:7], 0, v[158:159]
	s_mov_b32 m0, s92
	ds_read_b128 v[182:185], v206 offset:16384
	ds_read_b128 v[218:221], v206 offset:17408
	ds_read_b128 v[224:227], v206 offset:18432
	ds_read_b128 v[228:231], v206 offset:19456
	ds_read_b128 v[232:235], v206 offset:20480
	ds_read_b128 v[236:239], v206 offset:21504
	ds_read_b128 v[240:243], v206 offset:22528
	ds_read_b128 v[244:247], v206 offset:23552
	global_load_lds_dwordx4 v[186:187], off
	s_add_i32 m0, s92, 0x2000
	s_add_u32 s92, s6, 0x40000
	v_lshl_add_u64 v[248:249], s[6:7], 0, v[162:163]
	s_addc_u32 s93, s7, 0
	s_add_i32 s94, s71, s62
	global_load_lds_dwordx4 v[248:249], off
	v_lshl_add_u64 v[250:251], s[92:93], 0, v[158:159]
	s_mov_b32 m0, s94
	v_lshl_add_u64 v[252:253], s[12:13], 0, v[160:161]
	global_load_lds_dwordx4 v[250:251], off
	v_lshl_add_u64 v[250:251], s[92:93], 0, v[162:163]
	s_add_i32 m0, s94, 0x2000
	s_nop 0
	global_load_lds_dwordx4 v[250:251], off
	v_lshl_add_u64 v[250:251], s[12:13], 0, v[156:157]
	s_mov_b32 m0, s25
	s_nop 0
	global_load_lds_dwordx4 v[250:251], off
	s_mov_b32 m0, s63
	s_nop 0
	global_load_lds_dwordx4 v[252:253], off
	s_waitcnt vmcnt(8)
	s_waitcnt lgkmcnt(0)
	s_barrier
	s_setprio 1
	s_waitcnt lgkmcnt(0)
	v_mfma_f32_16x16x32_bf16 v[32:35], v[128:131], v[182:185], v[32:35]
	v_mfma_f32_16x16x32_bf16 v[36:39], v[136:139], v[182:185], v[36:39]
	v_mfma_f32_16x16x32_bf16 v[16:19], v[128:131], v[224:227], v[16:19]
	v_mfma_f32_16x16x32_bf16 v[20:23], v[136:139], v[224:227], v[20:23]
	v_mfma_f32_16x16x32_bf16 v[0:3], v[128:131], v[232:235], v[0:3]
	v_mfma_f32_16x16x32_bf16 v[4:7], v[136:139], v[232:235], v[4:7]
	v_mfma_f32_16x16x32_bf16 v[84:87], v[128:131], v[240:243], v[84:87]
	v_mfma_f32_16x16x32_bf16 v[92:95], v[136:139], v[240:243], v[92:95]
	v_mfma_f32_16x16x32_bf16 v[32:35], v[132:135], v[218:221], v[32:35]
	v_mfma_f32_16x16x32_bf16 v[36:39], v[140:143], v[218:221], v[36:39]
	v_mfma_f32_16x16x32_bf16 v[16:19], v[132:135], v[228:231], v[16:19]
	v_mfma_f32_16x16x32_bf16 v[20:23], v[140:143], v[228:231], v[20:23]
	v_mfma_f32_16x16x32_bf16 v[0:3], v[132:135], v[236:239], v[0:3]
	v_mfma_f32_16x16x32_bf16 v[4:7], v[140:143], v[236:239], v[4:7]
	v_mfma_f32_16x16x32_bf16 v[84:87], v[132:135], v[244:247], v[84:87]
	v_mfma_f32_16x16x32_bf16 v[92:95], v[140:143], v[244:247], v[92:95]
	v_mfma_f32_16x16x32_bf16 v[40:43], v[144:147], v[182:185], v[40:43]
	v_mfma_f32_16x16x32_bf16 v[44:47], v[152:155], v[182:185], v[44:47]
	v_mfma_f32_16x16x32_bf16 v[24:27], v[144:147], v[224:227], v[24:27]
	v_mfma_f32_16x16x32_bf16 v[28:31], v[152:155], v[224:227], v[28:31]
	v_mfma_f32_16x16x32_bf16 v[8:11], v[144:147], v[232:235], v[8:11]
	v_mfma_f32_16x16x32_bf16 v[12:15], v[152:155], v[232:235], v[12:15]
	v_mfma_f32_16x16x32_bf16 v[100:103], v[144:147], v[240:243], v[100:103]
	v_mfma_f32_16x16x32_bf16 v[108:111], v[152:155], v[240:243], v[108:111]
	v_mfma_f32_16x16x32_bf16 v[40:43], v[148:151], v[218:221], v[40:43]
	v_mfma_f32_16x16x32_bf16 v[44:47], v[178:181], v[218:221], v[44:47]
	v_mfma_f32_16x16x32_bf16 v[24:27], v[148:151], v[228:231], v[24:27]
	v_mfma_f32_16x16x32_bf16 v[28:31], v[178:181], v[228:231], v[28:31]
	v_mfma_f32_16x16x32_bf16 v[8:11], v[148:151], v[236:239], v[8:11]
	v_mfma_f32_16x16x32_bf16 v[12:15], v[178:181], v[236:239], v[12:15]
	v_mfma_f32_16x16x32_bf16 v[100:103], v[148:151], v[244:247], v[100:103]
	v_mfma_f32_16x16x32_bf16 v[108:111], v[178:181], v[244:247], v[108:111]
	s_setprio 0
	s_barrier
	s_add_i32 s92, 0, 0x18000
	s_add_i32 s93, 0, 0x1c000
	v_add_u32_e32 v140, s92, v188
	v_add_u32_e32 v164, s93, v188
	ds_read_b128 v[128:131], v140
	ds_read_b128 v[132:135], v140 offset:1024
	ds_read_b128 v[136:139], v140 offset:2048
	ds_read_b128 v[140:143], v140 offset:3072
	ds_read_b128 v[144:147], v164
	ds_read_b128 v[148:151], v164 offset:1024
	ds_read_b128 v[152:155], v164 offset:2048
	ds_read_b128 v[178:181], v164 offset:3072
	s_add_u32 s12, s12, 0x40000
	s_addc_u32 s13, s13, 0
	s_mov_b32 m0, s64
	v_lshl_add_u64 v[200:201], s[12:13], 0, v[156:157]
	ds_read_b128 v[182:185], v206 offset:32768
	ds_read_b128 v[218:221], v206 offset:33792
	ds_read_b128 v[224:227], v206 offset:34816
	ds_read_b128 v[228:231], v206 offset:35840
	ds_read_b128 v[232:235], v206 offset:36864
	ds_read_b128 v[236:239], v206 offset:37888
	ds_read_b128 v[240:243], v206 offset:38912
	ds_read_b128 v[244:247], v206 offset:39936
	global_load_lds_dwordx4 v[200:201], off
	v_lshl_add_u64 v[200:201], s[12:13], 0, v[160:161]
	s_mov_b32 m0, s65
	s_nop 0
	global_load_lds_dwordx4 v[200:201], off
	s_waitcnt vmcnt(8)
	s_waitcnt lgkmcnt(0)
	s_barrier
	s_setprio 1
	s_waitcnt lgkmcnt(0)
	v_mfma_f32_16x16x32_bf16 v[112:115], v[128:131], v[182:185], v[112:115]
	v_mfma_f32_16x16x32_bf16 v[116:119], v[136:139], v[182:185], v[116:119]
	v_mfma_f32_16x16x32_bf16 v[80:83], v[128:131], v[224:227], v[80:83]
	v_mfma_f32_16x16x32_bf16 v[88:91], v[136:139], v[224:227], v[88:91]
	v_mfma_f32_16x16x32_bf16 v[64:67], v[128:131], v[232:235], v[64:67]
	v_mfma_f32_16x16x32_bf16 v[68:71], v[136:139], v[232:235], v[68:71]
	v_mfma_f32_16x16x32_bf16 v[48:51], v[128:131], v[240:243], v[48:51]
	v_mfma_f32_16x16x32_bf16 v[52:55], v[136:139], v[240:243], v[52:55]
	v_mfma_f32_16x16x32_bf16 v[112:115], v[132:135], v[218:221], v[112:115]
	v_mfma_f32_16x16x32_bf16 v[116:119], v[140:143], v[218:221], v[116:119]
	v_mfma_f32_16x16x32_bf16 v[80:83], v[132:135], v[228:231], v[80:83]
	v_mfma_f32_16x16x32_bf16 v[88:91], v[140:143], v[228:231], v[88:91]
	v_mfma_f32_16x16x32_bf16 v[64:67], v[132:135], v[236:239], v[64:67]
	v_mfma_f32_16x16x32_bf16 v[68:71], v[140:143], v[236:239], v[68:71]
	v_mfma_f32_16x16x32_bf16 v[48:51], v[132:135], v[244:247], v[48:51]
	v_mfma_f32_16x16x32_bf16 v[52:55], v[140:143], v[244:247], v[52:55]
	v_mfma_f32_16x16x32_bf16 v[120:123], v[144:147], v[182:185], v[120:123]
	v_mfma_f32_16x16x32_bf16 v[124:127], v[152:155], v[182:185], v[124:127]
	v_mfma_f32_16x16x32_bf16 v[96:99], v[144:147], v[224:227], v[96:99]
	v_mfma_f32_16x16x32_bf16 v[104:107], v[152:155], v[224:227], v[104:107]
	v_mfma_f32_16x16x32_bf16 v[72:75], v[144:147], v[232:235], v[72:75]
	v_mfma_f32_16x16x32_bf16 v[76:79], v[152:155], v[232:235], v[76:79]
	v_mfma_f32_16x16x32_bf16 v[56:59], v[144:147], v[240:243], v[56:59]
	v_mfma_f32_16x16x32_bf16 v[60:63], v[152:155], v[240:243], v[60:63]
	v_mfma_f32_16x16x32_bf16 v[120:123], v[148:151], v[218:221], v[120:123]
	v_mfma_f32_16x16x32_bf16 v[124:127], v[178:181], v[218:221], v[124:127]
	v_mfma_f32_16x16x32_bf16 v[96:99], v[148:151], v[228:231], v[96:99]
	v_mfma_f32_16x16x32_bf16 v[104:107], v[178:181], v[228:231], v[104:107]
	v_mfma_f32_16x16x32_bf16 v[72:75], v[148:151], v[236:239], v[72:75]
	v_mfma_f32_16x16x32_bf16 v[76:79], v[178:181], v[236:239], v[76:79]
	v_mfma_f32_16x16x32_bf16 v[56:59], v[148:151], v[244:247], v[56:59]
	v_mfma_f32_16x16x32_bf16 v[60:63], v[178:181], v[244:247], v[60:63]
	s_setprio 0
	s_barrier
	s_add_i32 s12, s92, s62
	v_lshl_add_u64 v[186:187], v[186:187], 0, s[50:51]
	s_mov_b32 m0, s12
	ds_read_b128 v[182:185], v206 offset:49152
	ds_read_b128 v[218:221], v206 offset:50176
	ds_read_b128 v[224:227], v206 offset:51200
	ds_read_b128 v[228:231], v206 offset:52224
	ds_read_b128 v[232:235], v206 offset:53248
	ds_read_b128 v[236:239], v206 offset:54272
	ds_read_b128 v[240:243], v206 offset:55296
	ds_read_b128 v[244:247], v206 offset:56320
	global_load_lds_dwordx4 v[186:187], off
	s_add_i32 m0, s12, 0x2000
	s_add_u32 s6, s6, 0x40080
	v_lshl_add_u64 v[186:187], v[248:249], 0, s[50:51]
	s_addc_u32 s7, s7, 0
	s_add_i32 s12, s93, s62
	global_load_lds_dwordx4 v[186:187], off
	v_lshl_add_u64 v[186:187], s[6:7], 0, v[158:159]
	s_mov_b32 m0, s12
	s_nop 0
	global_load_lds_dwordx4 v[186:187], off
	v_lshl_add_u64 v[186:187], s[6:7], 0, v[162:163]
	s_add_i32 m0, s12, 0x2000
	s_nop 0
	global_load_lds_dwordx4 v[186:187], off
	v_lshl_add_u64 v[186:187], v[250:251], 0, s[50:51]
	s_mov_b32 m0, s78
	s_nop 0
	global_load_lds_dwordx4 v[186:187], off
	v_lshl_add_u64 v[186:187], v[252:253], 0, s[50:51]
	s_mov_b32 m0, s79
	s_nop 0
	global_load_lds_dwordx4 v[186:187], off
	s_add_i32 s91, s91, 2
	s_add_u32 s4, s4, 0x100
	s_addc_u32 s5, s5, 0
	s_add_u32 s85, s85, 0x100
	s_addc_u32 s90, s90, 0
	s_waitcnt vmcnt(8)
	s_waitcnt lgkmcnt(0)
	s_barrier
	s_setprio 1
	s_waitcnt lgkmcnt(0)
	v_mfma_f32_16x16x32_bf16 v[32:35], v[128:131], v[182:185], v[32:35]
	v_mfma_f32_16x16x32_bf16 v[36:39], v[136:139], v[182:185], v[36:39]
	v_mfma_f32_16x16x32_bf16 v[16:19], v[128:131], v[224:227], v[16:19]
	v_mfma_f32_16x16x32_bf16 v[20:23], v[136:139], v[224:227], v[20:23]
	v_mfma_f32_16x16x32_bf16 v[0:3], v[128:131], v[232:235], v[0:3]
	v_mfma_f32_16x16x32_bf16 v[4:7], v[136:139], v[232:235], v[4:7]
	v_mfma_f32_16x16x32_bf16 v[84:87], v[128:131], v[240:243], v[84:87]
	v_mfma_f32_16x16x32_bf16 v[92:95], v[136:139], v[240:243], v[92:95]
	v_mfma_f32_16x16x32_bf16 v[32:35], v[132:135], v[218:221], v[32:35]
	v_mfma_f32_16x16x32_bf16 v[36:39], v[140:143], v[218:221], v[36:39]
	v_mfma_f32_16x16x32_bf16 v[16:19], v[132:135], v[228:231], v[16:19]
	v_mfma_f32_16x16x32_bf16 v[20:23], v[140:143], v[228:231], v[20:23]
	v_mfma_f32_16x16x32_bf16 v[0:3], v[132:135], v[236:239], v[0:3]
	v_mfma_f32_16x16x32_bf16 v[4:7], v[140:143], v[236:239], v[4:7]
	v_mfma_f32_16x16x32_bf16 v[84:87], v[132:135], v[244:247], v[84:87]
	v_mfma_f32_16x16x32_bf16 v[92:95], v[140:143], v[244:247], v[92:95]
	v_mfma_f32_16x16x32_bf16 v[40:43], v[144:147], v[182:185], v[40:43]
	v_mfma_f32_16x16x32_bf16 v[44:47], v[152:155], v[182:185], v[44:47]
	v_mfma_f32_16x16x32_bf16 v[24:27], v[144:147], v[224:227], v[24:27]
	v_mfma_f32_16x16x32_bf16 v[28:31], v[152:155], v[224:227], v[28:31]
	v_mfma_f32_16x16x32_bf16 v[8:11], v[144:147], v[232:235], v[8:11]
	v_mfma_f32_16x16x32_bf16 v[12:15], v[152:155], v[232:235], v[12:15]
	v_mfma_f32_16x16x32_bf16 v[100:103], v[144:147], v[240:243], v[100:103]
	v_mfma_f32_16x16x32_bf16 v[108:111], v[152:155], v[240:243], v[108:111]
	v_mfma_f32_16x16x32_bf16 v[40:43], v[148:151], v[218:221], v[40:43]
	v_mfma_f32_16x16x32_bf16 v[44:47], v[178:181], v[218:221], v[44:47]
	v_mfma_f32_16x16x32_bf16 v[24:27], v[148:151], v[228:231], v[24:27]
	v_mfma_f32_16x16x32_bf16 v[28:31], v[178:181], v[228:231], v[28:31]
	v_mfma_f32_16x16x32_bf16 v[8:11], v[148:151], v[236:239], v[8:11]
	v_mfma_f32_16x16x32_bf16 v[12:15], v[178:181], v[236:239], v[12:15]
	v_mfma_f32_16x16x32_bf16 v[100:103], v[148:151], v[244:247], v[100:103]
	v_mfma_f32_16x16x32_bf16 v[108:111], v[178:181], v[244:247], v[108:111]
	s_setprio 0
	s_barrier
	s_cmp_gt_u32 s91, 13
	s_cbranch_scc0 .LBB0_476
	s_and_b64 vcc, exec, s[52:53]
	s_cbranch_vccz .LBB0_479
	s_barrier

.LBB0_1471:
	ds_read_b128 v[144:147], v159
	ds_read_b128 v[162:165], v159 offset:1024
	ds_read_b128 v[166:169], v159 offset:2048
	ds_read_b128 v[170:173], v159 offset:3072
	ds_read_b128 v[174:177], v160
	ds_read_b128 v[178:181], v160 offset:1024
	ds_read_b128 v[182:185], v160 offset:2048
	ds_read_b128 v[186:189], v160 offset:3072
	s_add_u32 s46, s44, 0xfffe0080
	s_addc_u32 s47, s45, -1
	s_cmp_eq_u32 s66, 4
	s_cselect_b32 s49, s10, s47
	s_cselect_b32 s48, s11, s46
	s_cselect_b32 s47, s19, s65
	s_cselect_b32 s46, s21, s64
	v_lshl_add_u64 v[224:225], s[44:45], 0, v[136:137]
	s_add_i32 m0, s43, 0xc000
	ds_read_b128 v[190:193], v161
	ds_read_b128 v[194:197], v161 offset:1024
	ds_read_b128 v[200:203], v161 offset:2048
	ds_read_b128 v[204:207], v161 offset:3072
	ds_read_b128 v[208:211], v161 offset:4096
	ds_read_b128 v[212:215], v161 offset:5120
	ds_read_b128 v[216:219], v161 offset:6144
	ds_read_b128 v[220:223], v161 offset:7168
	global_load_lds_dwordx4 v[224:225], off
	v_lshl_add_u64 v[224:225], s[44:45], 0, v[138:139]
	s_add_i32 m0, s43, 0xe000
	s_nop 0
	global_load_lds_dwordx4 v[224:225], off
	s_waitcnt vmcnt(8)
	s_waitcnt lgkmcnt(0)
	s_barrier
	s_setprio 1
	s_waitcnt lgkmcnt(0)
	v_mfma_f32_16x16x32_bf16 v[124:127], v[144:147], v[190:193], v[124:127]
	v_mfma_f32_16x16x32_bf16 v[120:123], v[166:169], v[190:193], v[120:123]
	v_mfma_f32_16x16x32_bf16 v[108:111], v[144:147], v[200:203], v[108:111]
	v_mfma_f32_16x16x32_bf16 v[104:107], v[166:169], v[200:203], v[104:107]
	v_mfma_f32_16x16x32_bf16 v[92:95], v[144:147], v[208:211], v[92:95]
	v_mfma_f32_16x16x32_bf16 v[88:91], v[166:169], v[208:211], v[88:91]
	v_mfma_f32_16x16x32_bf16 v[76:79], v[144:147], v[216:219], v[76:79]
	v_mfma_f32_16x16x32_bf16 v[72:75], v[166:169], v[216:219], v[72:75]
	v_mfma_f32_16x16x32_bf16 v[124:127], v[162:165], v[194:197], v[124:127]
	v_mfma_f32_16x16x32_bf16 v[120:123], v[170:173], v[194:197], v[120:123]
	v_mfma_f32_16x16x32_bf16 v[108:111], v[162:165], v[204:207], v[108:111]
	v_mfma_f32_16x16x32_bf16 v[104:107], v[170:173], v[204:207], v[104:107]
	v_mfma_f32_16x16x32_bf16 v[92:95], v[162:165], v[212:215], v[92:95]
	v_mfma_f32_16x16x32_bf16 v[88:91], v[170:173], v[212:215], v[88:91]
	v_mfma_f32_16x16x32_bf16 v[76:79], v[162:165], v[220:223], v[76:79]
	v_mfma_f32_16x16x32_bf16 v[72:75], v[170:173], v[220:223], v[72:75]
	v_mfma_f32_16x16x32_bf16 v[116:119], v[174:177], v[190:193], v[116:119]
	v_mfma_f32_16x16x32_bf16 v[112:115], v[182:185], v[190:193], v[112:115]
	v_mfma_f32_16x16x32_bf16 v[100:103], v[174:177], v[200:203], v[100:103]
	v_mfma_f32_16x16x32_bf16 v[96:99], v[182:185], v[200:203], v[96:99]
	v_mfma_f32_16x16x32_bf16 v[84:87], v[174:177], v[208:211], v[84:87]
	v_mfma_f32_16x16x32_bf16 v[80:83], v[182:185], v[208:211], v[80:83]
	v_mfma_f32_16x16x32_bf16 v[68:71], v[174:177], v[216:219], v[68:71]
	v_mfma_f32_16x16x32_bf16 v[64:67], v[182:185], v[216:219], v[64:67]
	v_mfma_f32_16x16x32_bf16 v[116:119], v[178:181], v[194:197], v[116:119]
	v_mfma_f32_16x16x32_bf16 v[112:115], v[186:189], v[194:197], v[112:115]
	v_mfma_f32_16x16x32_bf16 v[100:103], v[178:181], v[204:207], v[100:103]
	v_mfma_f32_16x16x32_bf16 v[96:99], v[186:189], v[204:207], v[96:99]
	v_mfma_f32_16x16x32_bf16 v[84:87], v[178:181], v[212:215], v[84:87]
	v_mfma_f32_16x16x32_bf16 v[80:83], v[186:189], v[212:215], v[80:83]
	v_mfma_f32_16x16x32_bf16 v[68:71], v[178:181], v[220:223], v[68:71]
	v_mfma_f32_16x16x32_bf16 v[64:67], v[186:189], v[220:223], v[64:67]
	s_setprio 0
	s_barrier
	s_add_i32 s67, s61, s52
	v_lshl_add_u64 v[224:225], s[46:47], 0, v[130:131]
	s_mov_b32 m0, s67
	ds_read_b128 v[190:193], v161 offset:16384
	ds_read_b128 v[194:197], v161 offset:17408
	ds_read_b128 v[200:203], v161 offset:18432
	ds_read_b128 v[204:207], v161 offset:19456
	ds_read_b128 v[208:211], v161 offset:20480
	ds_read_b128 v[212:215], v161 offset:21504
	ds_read_b128 v[216:219], v161 offset:22528
	ds_read_b128 v[220:223], v161 offset:23552
	global_load_lds_dwordx4 v[224:225], off
	s_add_i32 m0, s67, 0x2000
	s_add_u32 s70, s46, 0x20000
	v_lshl_add_u64 v[226:227], s[46:47], 0, v[134:135]
	s_addc_u32 s71, s47, 0
	s_add_i32 s67, s62, s52
	global_load_lds_dwordx4 v[226:227], off
	v_lshl_add_u64 v[228:229], s[70:71], 0, v[130:131]
	s_mov_b32 m0, s67
	v_lshl_add_u64 v[230:231], s[48:49], 0, v[132:133]
	global_load_lds_dwordx4 v[228:229], off
	v_lshl_add_u64 v[228:229], s[70:71], 0, v[134:135]
	s_add_i32 m0, s67, 0x2000
	s_nop 0
	global_load_lds_dwordx4 v[228:229], off
	v_lshl_add_u64 v[228:229], s[48:49], 0, v[128:129]
	s_mov_b32 m0, s43
	s_nop 0
	global_load_lds_dwordx4 v[228:229], off
	s_mov_b32 m0, s53
	s_nop 0
	global_load_lds_dwordx4 v[230:231], off
	s_waitcnt vmcnt(8)
	s_waitcnt lgkmcnt(0)
	s_barrier
	s_setprio 1
	s_waitcnt lgkmcnt(0)
	v_mfma_f32_16x16x32_bf16 v[60:63], v[144:147], v[190:193], v[60:63]
	v_mfma_f32_16x16x32_bf16 v[56:59], v[166:169], v[190:193], v[56:59]
	v_mfma_f32_16x16x32_bf16 v[44:47], v[144:147], v[200:203], v[44:47]
	v_mfma_f32_16x16x32_bf16 v[40:43], v[166:169], v[200:203], v[40:43]
	v_mfma_f32_16x16x32_bf16 v[28:31], v[144:147], v[208:211], v[28:31]
	v_mfma_f32_16x16x32_bf16 v[24:27], v[166:169], v[208:211], v[24:27]
	v_mfma_f32_16x16x32_bf16 v[12:15], v[144:147], v[216:219], v[12:15]
	v_mfma_f32_16x16x32_bf16 v[8:11], v[166:169], v[216:219], v[8:11]
	v_mfma_f32_16x16x32_bf16 v[60:63], v[162:165], v[194:197], v[60:63]
	v_mfma_f32_16x16x32_bf16 v[56:59], v[170:173], v[194:197], v[56:59]
	v_mfma_f32_16x16x32_bf16 v[44:47], v[162:165], v[204:207], v[44:47]
	v_mfma_f32_16x16x32_bf16 v[40:43], v[170:173], v[204:207], v[40:43]
	v_mfma_f32_16x16x32_bf16 v[28:31], v[162:165], v[212:215], v[28:31]
	v_mfma_f32_16x16x32_bf16 v[24:27], v[170:173], v[212:215], v[24:27]
	v_mfma_f32_16x16x32_bf16 v[12:15], v[162:165], v[220:223], v[12:15]
	v_mfma_f32_16x16x32_bf16 v[8:11], v[170:173], v[220:223], v[8:11]
	v_mfma_f32_16x16x32_bf16 v[52:55], v[174:177], v[190:193], v[52:55]
	v_mfma_f32_16x16x32_bf16 v[48:51], v[182:185], v[190:193], v[48:51]
	v_mfma_f32_16x16x32_bf16 v[36:39], v[174:177], v[200:203], v[36:39]
	v_mfma_f32_16x16x32_bf16 v[32:35], v[182:185], v[200:203], v[32:35]
	v_mfma_f32_16x16x32_bf16 v[20:23], v[174:177], v[208:211], v[20:23]
	v_mfma_f32_16x16x32_bf16 v[16:19], v[182:185], v[208:211], v[16:19]
	v_mfma_f32_16x16x32_bf16 v[4:7], v[174:177], v[216:219], v[4:7]
	v_mfma_f32_16x16x32_bf16 v[0:3], v[182:185], v[216:219], v[0:3]
	v_mfma_f32_16x16x32_bf16 v[52:55], v[178:181], v[194:197], v[52:55]
	v_mfma_f32_16x16x32_bf16 v[48:51], v[186:189], v[194:197], v[48:51]
	v_mfma_f32_16x16x32_bf16 v[36:39], v[178:181], v[204:207], v[36:39]
	v_mfma_f32_16x16x32_bf16 v[32:35], v[186:189], v[204:207], v[32:35]
	v_mfma_f32_16x16x32_bf16 v[20:23], v[178:181], v[212:215], v[20:23]
	v_mfma_f32_16x16x32_bf16 v[16:19], v[186:189], v[212:215], v[16:19]
	v_mfma_f32_16x16x32_bf16 v[4:7], v[178:181], v[220:223], v[4:7]
	v_mfma_f32_16x16x32_bf16 v[0:3], v[186:189], v[220:223], v[0:3]
	s_setprio 0
	s_barrier
	s_add_i32 s67, 0, 0x18000
	s_add_i32 s70, 0, 0x1c000
	v_add_u32_e32 v170, s67, v157
	v_add_u32_e32 v186, s70, v157
	ds_read_b128 v[144:147], v170
	ds_read_b128 v[162:165], v170 offset:1024
	ds_read_b128 v[166:169], v170 offset:2048
	ds_read_b128 v[170:173], v170 offset:3072
	ds_read_b128 v[174:177], v186
	ds_read_b128 v[178:181], v186 offset:1024
	ds_read_b128 v[182:185], v186 offset:2048
	ds_read_b128 v[186:189], v186 offset:3072
	s_add_u32 s48, s48, 0x20000
	s_addc_u32 s49, s49, 0
	s_mov_b32 m0, s54
	v_lshl_add_u64 v[232:233], s[48:49], 0, v[128:129]
	ds_read_b128 v[190:193], v161 offset:32768
	ds_read_b128 v[194:197], v161 offset:33792
	ds_read_b128 v[200:203], v161 offset:34816
	ds_read_b128 v[204:207], v161 offset:35840
	ds_read_b128 v[208:211], v161 offset:36864
	ds_read_b128 v[212:215], v161 offset:37888
	ds_read_b128 v[216:219], v161 offset:38912
	ds_read_b128 v[220:223], v161 offset:39936
	global_load_lds_dwordx4 v[232:233], off
	v_lshl_add_u64 v[232:233], s[48:49], 0, v[132:133]
	s_mov_b32 m0, s55
	s_nop 0
	global_load_lds_dwordx4 v[232:233], off
	s_waitcnt vmcnt(8)
	s_waitcnt lgkmcnt(0)
	s_barrier
	s_setprio 1
	s_waitcnt lgkmcnt(0)
	v_mfma_f32_16x16x32_bf16 v[124:127], v[144:147], v[190:193], v[124:127]
	v_mfma_f32_16x16x32_bf16 v[120:123], v[166:169], v[190:193], v[120:123]
	v_mfma_f32_16x16x32_bf16 v[108:111], v[144:147], v[200:203], v[108:111]
	v_mfma_f32_16x16x32_bf16 v[104:107], v[166:169], v[200:203], v[104:107]
	v_mfma_f32_16x16x32_bf16 v[92:95], v[144:147], v[208:211], v[92:95]
	v_mfma_f32_16x16x32_bf16 v[88:91], v[166:169], v[208:211], v[88:91]
	v_mfma_f32_16x16x32_bf16 v[76:79], v[144:147], v[216:219], v[76:79]
	v_mfma_f32_16x16x32_bf16 v[72:75], v[166:169], v[216:219], v[72:75]
	v_mfma_f32_16x16x32_bf16 v[124:127], v[162:165], v[194:197], v[124:127]
	v_mfma_f32_16x16x32_bf16 v[120:123], v[170:173], v[194:197], v[120:123]
	v_mfma_f32_16x16x32_bf16 v[108:111], v[162:165], v[204:207], v[108:111]
	v_mfma_f32_16x16x32_bf16 v[104:107], v[170:173], v[204:207], v[104:107]
	v_mfma_f32_16x16x32_bf16 v[92:95], v[162:165], v[212:215], v[92:95]
	v_mfma_f32_16x16x32_bf16 v[88:91], v[170:173], v[212:215], v[88:91]
	v_mfma_f32_16x16x32_bf16 v[76:79], v[162:165], v[220:223], v[76:79]
	v_mfma_f32_16x16x32_bf16 v[72:75], v[170:173], v[220:223], v[72:75]
	v_mfma_f32_16x16x32_bf16 v[116:119], v[174:177], v[190:193], v[116:119]
	v_mfma_f32_16x16x32_bf16 v[112:115], v[182:185], v[190:193], v[112:115]
	v_mfma_f32_16x16x32_bf16 v[100:103], v[174:177], v[200:203], v[100:103]
	v_mfma_f32_16x16x32_bf16 v[96:99], v[182:185], v[200:203], v[96:99]
	v_mfma_f32_16x16x32_bf16 v[84:87], v[174:177], v[208:211], v[84:87]
	v_mfma_f32_16x16x32_bf16 v[80:83], v[182:185], v[208:211], v[80:83]
	v_mfma_f32_16x16x32_bf16 v[68:71], v[174:177], v[216:219], v[68:71]
	v_mfma_f32_16x16x32_bf16 v[64:67], v[182:185], v[216:219], v[64:67]
	v_mfma_f32_16x16x32_bf16 v[116:119], v[178:181], v[194:197], v[116:119]
	v_mfma_f32_16x16x32_bf16 v[112:115], v[186:189], v[194:197], v[112:115]
	v_mfma_f32_16x16x32_bf16 v[100:103], v[178:181], v[204:207], v[100:103]
	v_mfma_f32_16x16x32_bf16 v[96:99], v[186:189], v[204:207], v[96:99]
	v_mfma_f32_16x16x32_bf16 v[84:87], v[178:181], v[212:215], v[84:87]
	v_mfma_f32_16x16x32_bf16 v[80:83], v[186:189], v[212:215], v[80:83]
	v_mfma_f32_16x16x32_bf16 v[68:71], v[178:181], v[220:223], v[68:71]
	v_mfma_f32_16x16x32_bf16 v[64:67], v[186:189], v[220:223], v[64:67]
	s_setprio 0
	s_barrier
	s_add_i32 s48, s67, s52
	v_lshl_add_u64 v[224:225], v[224:225], 0, s[8:9]
	s_mov_b32 m0, s48
	ds_read_b128 v[190:193], v161 offset:49152
	ds_read_b128 v[194:197], v161 offset:50176
	ds_read_b128 v[200:203], v161 offset:51200
	ds_read_b128 v[204:207], v161 offset:52224
	ds_read_b128 v[208:211], v161 offset:53248
	ds_read_b128 v[212:215], v161 offset:54272
	ds_read_b128 v[216:219], v161 offset:55296
	ds_read_b128 v[220:223], v161 offset:56320
	global_load_lds_dwordx4 v[224:225], off
	s_add_i32 m0, s48, 0x2000
	s_add_u32 s46, s46, 0x20080
	v_lshl_add_u64 v[224:225], v[226:227], 0, s[8:9]
	s_addc_u32 s47, s47, 0
	s_add_i32 s48, s70, s52
	global_load_lds_dwordx4 v[224:225], off
	v_lshl_add_u64 v[224:225], s[46:47], 0, v[130:131]
	s_mov_b32 m0, s48
	s_nop 0
	global_load_lds_dwordx4 v[224:225], off
	v_lshl_add_u64 v[224:225], s[46:47], 0, v[134:135]
	s_add_i32 m0, s48, 0x2000
	s_nop 0
	global_load_lds_dwordx4 v[224:225], off
	v_lshl_add_u64 v[224:225], v[228:229], 0, s[8:9]
	s_mov_b32 m0, s57
	s_nop 0
	global_load_lds_dwordx4 v[224:225], off
	v_lshl_add_u64 v[224:225], v[230:231], 0, s[8:9]
	s_mov_b32 m0, s58
	s_nop 0
	global_load_lds_dwordx4 v[224:225], off
	s_add_i32 s66, s66, 2
	s_add_u32 s44, s44, 0x100
	s_addc_u32 s45, s45, 0
	s_add_u32 s64, s64, 0x100
	s_addc_u32 s65, s65, 0
	s_waitcnt vmcnt(8)
	s_waitcnt lgkmcnt(0)
	s_barrier
	s_setprio 1
	s_waitcnt lgkmcnt(0)
	v_mfma_f32_16x16x32_bf16 v[60:63], v[144:147], v[190:193], v[60:63]
	v_mfma_f32_16x16x32_bf16 v[56:59], v[166:169], v[190:193], v[56:59]
	v_mfma_f32_16x16x32_bf16 v[44:47], v[144:147], v[200:203], v[44:47]
	v_mfma_f32_16x16x32_bf16 v[40:43], v[166:169], v[200:203], v[40:43]
	v_mfma_f32_16x16x32_bf16 v[28:31], v[144:147], v[208:211], v[28:31]
	v_mfma_f32_16x16x32_bf16 v[24:27], v[166:169], v[208:211], v[24:27]
	v_mfma_f32_16x16x32_bf16 v[12:15], v[144:147], v[216:219], v[12:15]
	v_mfma_f32_16x16x32_bf16 v[8:11], v[166:169], v[216:219], v[8:11]
	v_mfma_f32_16x16x32_bf16 v[60:63], v[162:165], v[194:197], v[60:63]
	v_mfma_f32_16x16x32_bf16 v[56:59], v[170:173], v[194:197], v[56:59]
	v_mfma_f32_16x16x32_bf16 v[44:47], v[162:165], v[204:207], v[44:47]
	v_mfma_f32_16x16x32_bf16 v[40:43], v[170:173], v[204:207], v[40:43]
	v_mfma_f32_16x16x32_bf16 v[28:31], v[162:165], v[212:215], v[28:31]
	v_mfma_f32_16x16x32_bf16 v[24:27], v[170:173], v[212:215], v[24:27]
	v_mfma_f32_16x16x32_bf16 v[12:15], v[162:165], v[220:223], v[12:15]
	v_mfma_f32_16x16x32_bf16 v[8:11], v[170:173], v[220:223], v[8:11]
	v_mfma_f32_16x16x32_bf16 v[52:55], v[174:177], v[190:193], v[52:55]
	v_mfma_f32_16x16x32_bf16 v[48:51], v[182:185], v[190:193], v[48:51]
	v_mfma_f32_16x16x32_bf16 v[36:39], v[174:177], v[200:203], v[36:39]
	v_mfma_f32_16x16x32_bf16 v[32:35], v[182:185], v[200:203], v[32:35]
	v_mfma_f32_16x16x32_bf16 v[20:23], v[174:177], v[208:211], v[20:23]
	v_mfma_f32_16x16x32_bf16 v[16:19], v[182:185], v[208:211], v[16:19]
	v_mfma_f32_16x16x32_bf16 v[4:7], v[174:177], v[216:219], v[4:7]
	v_mfma_f32_16x16x32_bf16 v[0:3], v[182:185], v[216:219], v[0:3]
	v_mfma_f32_16x16x32_bf16 v[52:55], v[178:181], v[194:197], v[52:55]
	v_mfma_f32_16x16x32_bf16 v[48:51], v[186:189], v[194:197], v[48:51]
	v_mfma_f32_16x16x32_bf16 v[36:39], v[178:181], v[204:207], v[36:39]
	v_mfma_f32_16x16x32_bf16 v[32:35], v[186:189], v[204:207], v[32:35]
	v_mfma_f32_16x16x32_bf16 v[20:23], v[178:181], v[212:215], v[20:23]
	v_mfma_f32_16x16x32_bf16 v[16:19], v[186:189], v[212:215], v[16:19]
	v_mfma_f32_16x16x32_bf16 v[4:7], v[178:181], v[220:223], v[4:7]
	v_mfma_f32_16x16x32_bf16 v[0:3], v[186:189], v[220:223], v[0:3]
	s_setprio 0
	s_barrier
	s_cmp_gt_u32 s66, 5
	s_cbranch_scc0 .LBB0_1471
	s_and_b64 vcc, exec, s[12:13]
	s_cbranch_vccz .LBB0_1474
	s_barrier

.LBB0_1495:
	ds_read_b128 v[144:147], v153
	ds_read_b128 v[156:159], v153 offset:1024
	ds_read_b128 v[160:163], v153 offset:2048
	ds_read_b128 v[164:167], v153 offset:3072
	ds_read_b128 v[168:171], v154
	ds_read_b128 v[172:175], v154 offset:1024
	ds_read_b128 v[176:179], v154 offset:2048
	ds_read_b128 v[180:183], v154 offset:3072
	s_add_u32 s48, s46, 0xfffe0080
	s_addc_u32 s49, s47, -1
	s_cmp_eq_u32 s66, 4
	s_cselect_b32 s51, s10, s49
	s_cselect_b32 s50, s11, s48
	s_cselect_b32 s49, s21, s65
	s_cselect_b32 s48, s25, s64
	v_lshl_add_u64 v[148:149], s[46:47], 0, v[136:137]
	s_add_i32 m0, s45, 0xc000
	ds_read_b128 v[184:187], v155
	ds_read_b128 v[188:191], v155 offset:1024
	ds_read_b128 v[192:195], v155 offset:2048
	ds_read_b128 v[200:203], v155 offset:3072
	ds_read_b128 v[204:207], v155 offset:4096
	ds_read_b128 v[208:211], v155 offset:5120
	ds_read_b128 v[212:215], v155 offset:6144
	ds_read_b128 v[216:219], v155 offset:7168
	global_load_lds_dwordx4 v[148:149], off
	v_lshl_add_u64 v[148:149], s[46:47], 0, v[138:139]
	s_add_i32 m0, s45, 0xe000
	s_nop 0
	global_load_lds_dwordx4 v[148:149], off
	s_waitcnt vmcnt(8)
	s_waitcnt lgkmcnt(0)
	s_barrier
	s_setprio 1
	s_waitcnt lgkmcnt(0)
	v_mfma_f32_16x16x32_bf16 v[124:127], v[144:147], v[184:187], v[124:127]
	v_mfma_f32_16x16x32_bf16 v[120:123], v[160:163], v[184:187], v[120:123]
	v_mfma_f32_16x16x32_bf16 v[108:111], v[144:147], v[192:195], v[108:111]
	v_mfma_f32_16x16x32_bf16 v[104:107], v[160:163], v[192:195], v[104:107]
	v_mfma_f32_16x16x32_bf16 v[92:95], v[144:147], v[204:207], v[92:95]
	v_mfma_f32_16x16x32_bf16 v[88:91], v[160:163], v[204:207], v[88:91]
	v_mfma_f32_16x16x32_bf16 v[76:79], v[144:147], v[212:215], v[76:79]
	v_mfma_f32_16x16x32_bf16 v[72:75], v[160:163], v[212:215], v[72:75]
	v_mfma_f32_16x16x32_bf16 v[124:127], v[156:159], v[188:191], v[124:127]
	v_mfma_f32_16x16x32_bf16 v[120:123], v[164:167], v[188:191], v[120:123]
	v_mfma_f32_16x16x32_bf16 v[108:111], v[156:159], v[200:203], v[108:111]
	v_mfma_f32_16x16x32_bf16 v[104:107], v[164:167], v[200:203], v[104:107]
	v_mfma_f32_16x16x32_bf16 v[92:95], v[156:159], v[208:211], v[92:95]
	v_mfma_f32_16x16x32_bf16 v[88:91], v[164:167], v[208:211], v[88:91]
	v_mfma_f32_16x16x32_bf16 v[76:79], v[156:159], v[216:219], v[76:79]
	v_mfma_f32_16x16x32_bf16 v[72:75], v[164:167], v[216:219], v[72:75]
	v_mfma_f32_16x16x32_bf16 v[116:119], v[168:171], v[184:187], v[116:119]
	v_mfma_f32_16x16x32_bf16 v[112:115], v[176:179], v[184:187], v[112:115]
	v_mfma_f32_16x16x32_bf16 v[100:103], v[168:171], v[192:195], v[100:103]
	v_mfma_f32_16x16x32_bf16 v[96:99], v[176:179], v[192:195], v[96:99]
	v_mfma_f32_16x16x32_bf16 v[84:87], v[168:171], v[204:207], v[84:87]
	v_mfma_f32_16x16x32_bf16 v[80:83], v[176:179], v[204:207], v[80:83]
	v_mfma_f32_16x16x32_bf16 v[68:71], v[168:171], v[212:215], v[68:71]
	v_mfma_f32_16x16x32_bf16 v[64:67], v[176:179], v[212:215], v[64:67]
	v_mfma_f32_16x16x32_bf16 v[116:119], v[172:175], v[188:191], v[116:119]
	v_mfma_f32_16x16x32_bf16 v[112:115], v[180:183], v[188:191], v[112:115]
	v_mfma_f32_16x16x32_bf16 v[100:103], v[172:175], v[200:203], v[100:103]
	v_mfma_f32_16x16x32_bf16 v[96:99], v[180:183], v[200:203], v[96:99]
	v_mfma_f32_16x16x32_bf16 v[84:87], v[172:175], v[208:211], v[84:87]
	v_mfma_f32_16x16x32_bf16 v[80:83], v[180:183], v[208:211], v[80:83]
	v_mfma_f32_16x16x32_bf16 v[68:71], v[172:175], v[216:219], v[68:71]
	v_mfma_f32_16x16x32_bf16 v[64:67], v[180:183], v[216:219], v[64:67]
	s_setprio 0
	s_barrier
	s_add_i32 s67, s61, s52
	v_lshl_add_u64 v[148:149], s[48:49], 0, v[130:131]
	s_mov_b32 m0, s67
	ds_read_b128 v[184:187], v155 offset:16384
	ds_read_b128 v[188:191], v155 offset:17408
	ds_read_b128 v[192:195], v155 offset:18432
	ds_read_b128 v[200:203], v155 offset:19456
	ds_read_b128 v[204:207], v155 offset:20480
	ds_read_b128 v[208:211], v155 offset:21504
	ds_read_b128 v[212:215], v155 offset:22528
	ds_read_b128 v[216:219], v155 offset:23552
	global_load_lds_dwordx4 v[148:149], off
	s_add_i32 m0, s67, 0x2000
	s_add_u32 s70, s48, 0x20000
	v_lshl_add_u64 v[196:197], s[48:49], 0, v[134:135]
	s_addc_u32 s71, s49, 0
	s_add_i32 s67, s62, s52
	global_load_lds_dwordx4 v[196:197], off
	v_lshl_add_u64 v[220:221], s[70:71], 0, v[130:131]
	s_mov_b32 m0, s67
	v_lshl_add_u64 v[222:223], s[50:51], 0, v[132:133]
	global_load_lds_dwordx4 v[220:221], off
	v_lshl_add_u64 v[220:221], s[70:71], 0, v[134:135]
	s_add_i32 m0, s67, 0x2000
	s_nop 0
	global_load_lds_dwordx4 v[220:221], off
	v_lshl_add_u64 v[220:221], s[50:51], 0, v[128:129]
	s_mov_b32 m0, s45
	s_nop 0
	global_load_lds_dwordx4 v[220:221], off
	s_mov_b32 m0, s53
	s_nop 0
	global_load_lds_dwordx4 v[222:223], off
	s_waitcnt vmcnt(8)
	s_waitcnt lgkmcnt(0)
	s_barrier
	s_setprio 1
	s_waitcnt lgkmcnt(0)
	v_mfma_f32_16x16x32_bf16 v[60:63], v[144:147], v[184:187], v[60:63]
	v_mfma_f32_16x16x32_bf16 v[56:59], v[160:163], v[184:187], v[56:59]
	v_mfma_f32_16x16x32_bf16 v[44:47], v[144:147], v[192:195], v[44:47]
	v_mfma_f32_16x16x32_bf16 v[40:43], v[160:163], v[192:195], v[40:43]
	v_mfma_f32_16x16x32_bf16 v[28:31], v[144:147], v[204:207], v[28:31]
	v_mfma_f32_16x16x32_bf16 v[24:27], v[160:163], v[204:207], v[24:27]
	v_mfma_f32_16x16x32_bf16 v[12:15], v[144:147], v[212:215], v[12:15]
	v_mfma_f32_16x16x32_bf16 v[8:11], v[160:163], v[212:215], v[8:11]
	v_mfma_f32_16x16x32_bf16 v[60:63], v[156:159], v[188:191], v[60:63]
	v_mfma_f32_16x16x32_bf16 v[56:59], v[164:167], v[188:191], v[56:59]
	v_mfma_f32_16x16x32_bf16 v[44:47], v[156:159], v[200:203], v[44:47]
	v_mfma_f32_16x16x32_bf16 v[40:43], v[164:167], v[200:203], v[40:43]
	v_mfma_f32_16x16x32_bf16 v[28:31], v[156:159], v[208:211], v[28:31]
	v_mfma_f32_16x16x32_bf16 v[24:27], v[164:167], v[208:211], v[24:27]
	v_mfma_f32_16x16x32_bf16 v[12:15], v[156:159], v[216:219], v[12:15]
	v_mfma_f32_16x16x32_bf16 v[8:11], v[164:167], v[216:219], v[8:11]
	v_mfma_f32_16x16x32_bf16 v[52:55], v[168:171], v[184:187], v[52:55]
	v_mfma_f32_16x16x32_bf16 v[48:51], v[176:179], v[184:187], v[48:51]
	v_mfma_f32_16x16x32_bf16 v[36:39], v[168:171], v[192:195], v[36:39]
	v_mfma_f32_16x16x32_bf16 v[32:35], v[176:179], v[192:195], v[32:35]
	v_mfma_f32_16x16x32_bf16 v[20:23], v[168:171], v[204:207], v[20:23]
	v_mfma_f32_16x16x32_bf16 v[16:19], v[176:179], v[204:207], v[16:19]
	v_mfma_f32_16x16x32_bf16 v[4:7], v[168:171], v[212:215], v[4:7]
	v_mfma_f32_16x16x32_bf16 v[0:3], v[176:179], v[212:215], v[0:3]
	v_mfma_f32_16x16x32_bf16 v[52:55], v[172:175], v[188:191], v[52:55]
	v_mfma_f32_16x16x32_bf16 v[48:51], v[180:183], v[188:191], v[48:51]
	v_mfma_f32_16x16x32_bf16 v[36:39], v[172:175], v[200:203], v[36:39]
	v_mfma_f32_16x16x32_bf16 v[32:35], v[180:183], v[200:203], v[32:35]
	v_mfma_f32_16x16x32_bf16 v[20:23], v[172:175], v[208:211], v[20:23]
	v_mfma_f32_16x16x32_bf16 v[16:19], v[180:183], v[208:211], v[16:19]
	v_mfma_f32_16x16x32_bf16 v[4:7], v[172:175], v[216:219], v[4:7]
	v_mfma_f32_16x16x32_bf16 v[0:3], v[180:183], v[216:219], v[0:3]
	s_setprio 0
	s_barrier
	s_add_i32 s67, 0, 0x18000
	s_add_i32 s70, 0, 0x1c000
	v_add_u32_e32 v164, s67, v151
	v_add_u32_e32 v180, s70, v151
	ds_read_b128 v[144:147], v164
	ds_read_b128 v[156:159], v164 offset:1024
	ds_read_b128 v[160:163], v164 offset:2048
	ds_read_b128 v[164:167], v164 offset:3072
	ds_read_b128 v[168:171], v180
	ds_read_b128 v[172:175], v180 offset:1024
	ds_read_b128 v[176:179], v180 offset:2048
	ds_read_b128 v[180:183], v180 offset:3072
	s_add_u32 s50, s50, 0x20000
	s_addc_u32 s51, s51, 0
	s_mov_b32 m0, s54
	v_lshl_add_u64 v[224:225], s[50:51], 0, v[128:129]
	ds_read_b128 v[184:187], v155 offset:32768
	ds_read_b128 v[188:191], v155 offset:33792
	ds_read_b128 v[192:195], v155 offset:34816
	ds_read_b128 v[200:203], v155 offset:35840
	ds_read_b128 v[204:207], v155 offset:36864
	ds_read_b128 v[208:211], v155 offset:37888
	ds_read_b128 v[212:215], v155 offset:38912
	ds_read_b128 v[216:219], v155 offset:39936
	global_load_lds_dwordx4 v[224:225], off
	v_lshl_add_u64 v[224:225], s[50:51], 0, v[132:133]
	s_mov_b32 m0, s55
	s_nop 0
	global_load_lds_dwordx4 v[224:225], off
	s_waitcnt vmcnt(8)
	s_waitcnt lgkmcnt(0)
	s_barrier
	s_setprio 1
	s_waitcnt lgkmcnt(0)
	v_mfma_f32_16x16x32_bf16 v[124:127], v[144:147], v[184:187], v[124:127]
	v_mfma_f32_16x16x32_bf16 v[120:123], v[160:163], v[184:187], v[120:123]
	v_mfma_f32_16x16x32_bf16 v[108:111], v[144:147], v[192:195], v[108:111]
	v_mfma_f32_16x16x32_bf16 v[104:107], v[160:163], v[192:195], v[104:107]
	v_mfma_f32_16x16x32_bf16 v[92:95], v[144:147], v[204:207], v[92:95]
	v_mfma_f32_16x16x32_bf16 v[88:91], v[160:163], v[204:207], v[88:91]
	v_mfma_f32_16x16x32_bf16 v[76:79], v[144:147], v[212:215], v[76:79]
	v_mfma_f32_16x16x32_bf16 v[72:75], v[160:163], v[212:215], v[72:75]
	v_mfma_f32_16x16x32_bf16 v[124:127], v[156:159], v[188:191], v[124:127]
	v_mfma_f32_16x16x32_bf16 v[120:123], v[164:167], v[188:191], v[120:123]
	v_mfma_f32_16x16x32_bf16 v[108:111], v[156:159], v[200:203], v[108:111]
	v_mfma_f32_16x16x32_bf16 v[104:107], v[164:167], v[200:203], v[104:107]
	v_mfma_f32_16x16x32_bf16 v[92:95], v[156:159], v[208:211], v[92:95]
	v_mfma_f32_16x16x32_bf16 v[88:91], v[164:167], v[208:211], v[88:91]
	v_mfma_f32_16x16x32_bf16 v[76:79], v[156:159], v[216:219], v[76:79]
	v_mfma_f32_16x16x32_bf16 v[72:75], v[164:167], v[216:219], v[72:75]
	v_mfma_f32_16x16x32_bf16 v[116:119], v[168:171], v[184:187], v[116:119]
	v_mfma_f32_16x16x32_bf16 v[112:115], v[176:179], v[184:187], v[112:115]
	v_mfma_f32_16x16x32_bf16 v[100:103], v[168:171], v[192:195], v[100:103]
	v_mfma_f32_16x16x32_bf16 v[96:99], v[176:179], v[192:195], v[96:99]
	v_mfma_f32_16x16x32_bf16 v[84:87], v[168:171], v[204:207], v[84:87]
	v_mfma_f32_16x16x32_bf16 v[80:83], v[176:179], v[204:207], v[80:83]
	v_mfma_f32_16x16x32_bf16 v[68:71], v[168:171], v[212:215], v[68:71]
	v_mfma_f32_16x16x32_bf16 v[64:67], v[176:179], v[212:215], v[64:67]
	v_mfma_f32_16x16x32_bf16 v[116:119], v[172:175], v[188:191], v[116:119]
	v_mfma_f32_16x16x32_bf16 v[112:115], v[180:183], v[188:191], v[112:115]
	v_mfma_f32_16x16x32_bf16 v[100:103], v[172:175], v[200:203], v[100:103]
	v_mfma_f32_16x16x32_bf16 v[96:99], v[180:183], v[200:203], v[96:99]
	v_mfma_f32_16x16x32_bf16 v[84:87], v[172:175], v[208:211], v[84:87]
	v_mfma_f32_16x16x32_bf16 v[80:83], v[180:183], v[208:211], v[80:83]
	v_mfma_f32_16x16x32_bf16 v[68:71], v[172:175], v[216:219], v[68:71]
	v_mfma_f32_16x16x32_bf16 v[64:67], v[180:183], v[216:219], v[64:67]
	s_setprio 0
	s_barrier
	s_add_i32 s50, s67, s52
	v_lshl_add_u64 v[148:149], v[148:149], 0, s[6:7]
	s_mov_b32 m0, s50
	ds_read_b128 v[184:187], v155 offset:49152
	ds_read_b128 v[188:191], v155 offset:50176
	ds_read_b128 v[192:195], v155 offset:51200
	ds_read_b128 v[200:203], v155 offset:52224
	ds_read_b128 v[204:207], v155 offset:53248
	ds_read_b128 v[208:211], v155 offset:54272
	ds_read_b128 v[212:215], v155 offset:55296
	ds_read_b128 v[216:219], v155 offset:56320
	global_load_lds_dwordx4 v[148:149], off
	s_add_i32 m0, s50, 0x2000
	s_add_u32 s48, s48, 0x20080
	v_lshl_add_u64 v[148:149], v[196:197], 0, s[6:7]
	s_addc_u32 s49, s49, 0
	s_add_i32 s50, s70, s52
	global_load_lds_dwordx4 v[148:149], off
	v_lshl_add_u64 v[148:149], s[48:49], 0, v[130:131]
	s_mov_b32 m0, s50
	s_nop 0
	global_load_lds_dwordx4 v[148:149], off
	v_lshl_add_u64 v[148:149], s[48:49], 0, v[134:135]
	s_add_i32 m0, s50, 0x2000
	s_nop 0
	global_load_lds_dwordx4 v[148:149], off
	v_lshl_add_u64 v[148:149], v[220:221], 0, s[6:7]
	s_mov_b32 m0, s57
	s_nop 0
	global_load_lds_dwordx4 v[148:149], off
	v_lshl_add_u64 v[148:149], v[222:223], 0, s[6:7]
	s_mov_b32 m0, s58
	s_nop 0
	global_load_lds_dwordx4 v[148:149], off
	s_add_i32 s66, s66, 2
	s_add_u32 s46, s46, 0x100
	s_addc_u32 s47, s47, 0
	s_add_u32 s64, s64, 0x100
	s_addc_u32 s65, s65, 0
	s_waitcnt vmcnt(8)
	s_waitcnt lgkmcnt(0)
	s_barrier
	s_setprio 1
	s_waitcnt lgkmcnt(0)
	v_mfma_f32_16x16x32_bf16 v[60:63], v[144:147], v[184:187], v[60:63]
	v_mfma_f32_16x16x32_bf16 v[56:59], v[160:163], v[184:187], v[56:59]
	v_mfma_f32_16x16x32_bf16 v[44:47], v[144:147], v[192:195], v[44:47]
	v_mfma_f32_16x16x32_bf16 v[40:43], v[160:163], v[192:195], v[40:43]
	v_mfma_f32_16x16x32_bf16 v[28:31], v[144:147], v[204:207], v[28:31]
	v_mfma_f32_16x16x32_bf16 v[24:27], v[160:163], v[204:207], v[24:27]
	v_mfma_f32_16x16x32_bf16 v[12:15], v[144:147], v[212:215], v[12:15]
	v_mfma_f32_16x16x32_bf16 v[8:11], v[160:163], v[212:215], v[8:11]
	v_mfma_f32_16x16x32_bf16 v[60:63], v[156:159], v[188:191], v[60:63]
	v_mfma_f32_16x16x32_bf16 v[56:59], v[164:167], v[188:191], v[56:59]
	v_mfma_f32_16x16x32_bf16 v[44:47], v[156:159], v[200:203], v[44:47]
	v_mfma_f32_16x16x32_bf16 v[40:43], v[164:167], v[200:203], v[40:43]
	v_mfma_f32_16x16x32_bf16 v[28:31], v[156:159], v[208:211], v[28:31]
	v_mfma_f32_16x16x32_bf16 v[24:27], v[164:167], v[208:211], v[24:27]
	v_mfma_f32_16x16x32_bf16 v[12:15], v[156:159], v[216:219], v[12:15]
	v_mfma_f32_16x16x32_bf16 v[8:11], v[164:167], v[216:219], v[8:11]
	v_mfma_f32_16x16x32_bf16 v[52:55], v[168:171], v[184:187], v[52:55]
	v_mfma_f32_16x16x32_bf16 v[48:51], v[176:179], v[184:187], v[48:51]
	v_mfma_f32_16x16x32_bf16 v[36:39], v[168:171], v[192:195], v[36:39]
	v_mfma_f32_16x16x32_bf16 v[32:35], v[176:179], v[192:195], v[32:35]
	v_mfma_f32_16x16x32_bf16 v[20:23], v[168:171], v[204:207], v[20:23]
	v_mfma_f32_16x16x32_bf16 v[16:19], v[176:179], v[204:207], v[16:19]
	v_mfma_f32_16x16x32_bf16 v[4:7], v[168:171], v[212:215], v[4:7]
	v_mfma_f32_16x16x32_bf16 v[0:3], v[176:179], v[212:215], v[0:3]
	v_mfma_f32_16x16x32_bf16 v[52:55], v[172:175], v[188:191], v[52:55]
	v_mfma_f32_16x16x32_bf16 v[48:51], v[180:183], v[188:191], v[48:51]
	v_mfma_f32_16x16x32_bf16 v[36:39], v[172:175], v[200:203], v[36:39]
	v_mfma_f32_16x16x32_bf16 v[32:35], v[180:183], v[200:203], v[32:35]
	v_mfma_f32_16x16x32_bf16 v[20:23], v[172:175], v[208:211], v[20:23]
	v_mfma_f32_16x16x32_bf16 v[16:19], v[180:183], v[208:211], v[16:19]
	v_mfma_f32_16x16x32_bf16 v[4:7], v[172:175], v[216:219], v[4:7]
	v_mfma_f32_16x16x32_bf16 v[0:3], v[180:183], v[216:219], v[0:3]
	s_setprio 0
	s_barrier
	s_cmp_gt_u32 s66, 5
	s_cbranch_scc0 .LBB0_1495
	s_and_b64 vcc, exec, s[8:9]
	s_cbranch_vccz .LBB0_1498
	s_barrier

.LBB0_1576:
	ds_read_b128 v[88:91], v175
	ds_read_b128 v[92:95], v175 offset:1024
	ds_read_b128 v[96:99], v175 offset:2048
	ds_read_b128 v[100:103], v175 offset:3072
	ds_read_b128 v[160:163], v176
	ds_read_b128 v[164:167], v176 offset:1024
	ds_read_b128 v[168:171], v176 offset:2048
	ds_read_b128 v[180:183], v176 offset:3072
	s_add_u32 s50, s48, 0xfffc0080
	s_addc_u32 s51, s49, -1
	s_cmp_eq_u32 s76, 12
	s_cselect_b32 s53, s10, s51
	s_cselect_b32 s52, s11, s50
	s_cselect_b32 s51, s21, s75
	s_cselect_b32 s50, s25, s45
	v_lshl_add_u64 v[196:197], s[48:49], 0, v[152:153]
	s_add_i32 m0, s47, 0xc000
	ds_read_b128 v[184:187], v177
	ds_read_b128 v[188:191], v177 offset:1024
	ds_read_b128 v[192:195], v177 offset:2048
	ds_read_b128 v[200:203], v177 offset:3072
	ds_read_b128 v[204:207], v177 offset:4096
	ds_read_b128 v[208:211], v177 offset:5120
	ds_read_b128 v[212:215], v177 offset:6144
	ds_read_b128 v[216:219], v177 offset:7168
	global_load_lds_dwordx4 v[196:197], off
	v_lshl_add_u64 v[196:197], s[48:49], 0, v[154:155]
	s_add_i32 m0, s47, 0xe000
	s_nop 0
	global_load_lds_dwordx4 v[196:197], off
	s_waitcnt vmcnt(8)
	s_waitcnt lgkmcnt(0)
	s_barrier
	s_setprio 1
	s_waitcnt lgkmcnt(0)
	v_mfma_f32_16x16x32_bf16 v[140:143], v[88:91], v[184:187], v[140:143]
	v_mfma_f32_16x16x32_bf16 v[136:139], v[96:99], v[184:187], v[136:139]
	v_mfma_f32_16x16x32_bf16 v[124:127], v[88:91], v[192:195], v[124:127]
	v_mfma_f32_16x16x32_bf16 v[120:123], v[96:99], v[192:195], v[120:123]
	v_mfma_f32_16x16x32_bf16 v[108:111], v[88:91], v[204:207], v[108:111]
	v_mfma_f32_16x16x32_bf16 v[104:107], v[96:99], v[204:207], v[104:107]
	v_mfma_f32_16x16x32_bf16 v[76:79], v[88:91], v[212:215], v[76:79]
	v_mfma_f32_16x16x32_bf16 v[72:75], v[96:99], v[212:215], v[72:75]
	v_mfma_f32_16x16x32_bf16 v[140:143], v[92:95], v[188:191], v[140:143]
	v_mfma_f32_16x16x32_bf16 v[136:139], v[100:103], v[188:191], v[136:139]
	v_mfma_f32_16x16x32_bf16 v[124:127], v[92:95], v[200:203], v[124:127]
	v_mfma_f32_16x16x32_bf16 v[120:123], v[100:103], v[200:203], v[120:123]
	v_mfma_f32_16x16x32_bf16 v[108:111], v[92:95], v[208:211], v[108:111]
	v_mfma_f32_16x16x32_bf16 v[104:107], v[100:103], v[208:211], v[104:107]
	v_mfma_f32_16x16x32_bf16 v[76:79], v[92:95], v[216:219], v[76:79]
	v_mfma_f32_16x16x32_bf16 v[72:75], v[100:103], v[216:219], v[72:75]
	v_mfma_f32_16x16x32_bf16 v[132:135], v[160:163], v[184:187], v[132:135]
	v_mfma_f32_16x16x32_bf16 v[128:131], v[168:171], v[184:187], v[128:131]
	v_mfma_f32_16x16x32_bf16 v[116:119], v[160:163], v[192:195], v[116:119]
	v_mfma_f32_16x16x32_bf16 v[112:115], v[168:171], v[192:195], v[112:115]
	v_mfma_f32_16x16x32_bf16 v[84:87], v[160:163], v[204:207], v[84:87]
	v_mfma_f32_16x16x32_bf16 v[80:83], v[168:171], v[204:207], v[80:83]
	v_mfma_f32_16x16x32_bf16 v[68:71], v[160:163], v[212:215], v[68:71]
	v_mfma_f32_16x16x32_bf16 v[64:67], v[168:171], v[212:215], v[64:67]
	v_mfma_f32_16x16x32_bf16 v[132:135], v[164:167], v[188:191], v[132:135]
	v_mfma_f32_16x16x32_bf16 v[128:131], v[180:183], v[188:191], v[128:131]
	v_mfma_f32_16x16x32_bf16 v[116:119], v[164:167], v[200:203], v[116:119]
	v_mfma_f32_16x16x32_bf16 v[112:115], v[180:183], v[200:203], v[112:115]
	v_mfma_f32_16x16x32_bf16 v[84:87], v[164:167], v[208:211], v[84:87]
	v_mfma_f32_16x16x32_bf16 v[80:83], v[180:183], v[208:211], v[80:83]
	v_mfma_f32_16x16x32_bf16 v[68:71], v[164:167], v[216:219], v[68:71]
	v_mfma_f32_16x16x32_bf16 v[64:67], v[180:183], v[216:219], v[64:67]
	s_setprio 0
	s_barrier
	s_add_i32 s77, s67, s55
	v_lshl_add_u64 v[196:197], s[50:51], 0, v[146:147]
	s_mov_b32 m0, s77
	ds_read_b128 v[184:187], v177 offset:16384
	ds_read_b128 v[188:191], v177 offset:17408
	ds_read_b128 v[192:195], v177 offset:18432
	ds_read_b128 v[200:203], v177 offset:19456
	ds_read_b128 v[204:207], v177 offset:20480
	ds_read_b128 v[208:211], v177 offset:21504
	ds_read_b128 v[212:215], v177 offset:22528
	ds_read_b128 v[216:219], v177 offset:23552
	global_load_lds_dwordx4 v[196:197], off
	s_add_i32 m0, s77, 0x2000
	s_add_u32 s78, s50, 0x40000
	v_lshl_add_u64 v[220:221], s[50:51], 0, v[150:151]
	s_addc_u32 s79, s51, 0
	s_add_i32 s77, s70, s55
	global_load_lds_dwordx4 v[220:221], off
	v_lshl_add_u64 v[222:223], s[78:79], 0, v[146:147]
	s_mov_b32 m0, s77
	v_lshl_add_u64 v[224:225], s[52:53], 0, v[148:149]
	global_load_lds_dwordx4 v[222:223], off
	v_lshl_add_u64 v[222:223], s[78:79], 0, v[150:151]
	s_add_i32 m0, s77, 0x2000
	s_nop 0
	global_load_lds_dwordx4 v[222:223], off
	v_lshl_add_u64 v[222:223], s[52:53], 0, v[144:145]
	s_mov_b32 m0, s47
	s_nop 0
	global_load_lds_dwordx4 v[222:223], off
	s_mov_b32 m0, s56
	s_nop 0
	global_load_lds_dwordx4 v[224:225], off
	s_waitcnt vmcnt(8)
	s_waitcnt lgkmcnt(0)
	s_barrier
	s_setprio 1
	s_waitcnt lgkmcnt(0)
	v_mfma_f32_16x16x32_bf16 v[60:63], v[88:91], v[184:187], v[60:63]
	v_mfma_f32_16x16x32_bf16 v[56:59], v[96:99], v[184:187], v[56:59]
	v_mfma_f32_16x16x32_bf16 v[44:47], v[88:91], v[192:195], v[44:47]
	v_mfma_f32_16x16x32_bf16 v[40:43], v[96:99], v[192:195], v[40:43]
	v_mfma_f32_16x16x32_bf16 v[28:31], v[88:91], v[204:207], v[28:31]
	v_mfma_f32_16x16x32_bf16 v[24:27], v[96:99], v[204:207], v[24:27]
	v_mfma_f32_16x16x32_bf16 v[12:15], v[88:91], v[212:215], v[12:15]
	v_mfma_f32_16x16x32_bf16 v[8:11], v[96:99], v[212:215], v[8:11]
	v_mfma_f32_16x16x32_bf16 v[60:63], v[92:95], v[188:191], v[60:63]
	v_mfma_f32_16x16x32_bf16 v[56:59], v[100:103], v[188:191], v[56:59]
	v_mfma_f32_16x16x32_bf16 v[44:47], v[92:95], v[200:203], v[44:47]
	v_mfma_f32_16x16x32_bf16 v[40:43], v[100:103], v[200:203], v[40:43]
	v_mfma_f32_16x16x32_bf16 v[28:31], v[92:95], v[208:211], v[28:31]
	v_mfma_f32_16x16x32_bf16 v[24:27], v[100:103], v[208:211], v[24:27]
	v_mfma_f32_16x16x32_bf16 v[12:15], v[92:95], v[216:219], v[12:15]
	v_mfma_f32_16x16x32_bf16 v[8:11], v[100:103], v[216:219], v[8:11]
	v_mfma_f32_16x16x32_bf16 v[52:55], v[160:163], v[184:187], v[52:55]
	v_mfma_f32_16x16x32_bf16 v[48:51], v[168:171], v[184:187], v[48:51]
	v_mfma_f32_16x16x32_bf16 v[36:39], v[160:163], v[192:195], v[36:39]
	v_mfma_f32_16x16x32_bf16 v[32:35], v[168:171], v[192:195], v[32:35]
	v_mfma_f32_16x16x32_bf16 v[20:23], v[160:163], v[204:207], v[20:23]
	v_mfma_f32_16x16x32_bf16 v[16:19], v[168:171], v[204:207], v[16:19]
	v_mfma_f32_16x16x32_bf16 v[4:7], v[160:163], v[212:215], v[4:7]
	v_mfma_f32_16x16x32_bf16 v[0:3], v[168:171], v[212:215], v[0:3]
	v_mfma_f32_16x16x32_bf16 v[52:55], v[164:167], v[188:191], v[52:55]
	v_mfma_f32_16x16x32_bf16 v[48:51], v[180:183], v[188:191], v[48:51]
	v_mfma_f32_16x16x32_bf16 v[36:39], v[164:167], v[200:203], v[36:39]
	v_mfma_f32_16x16x32_bf16 v[32:35], v[180:183], v[200:203], v[32:35]
	v_mfma_f32_16x16x32_bf16 v[20:23], v[164:167], v[208:211], v[20:23]
	v_mfma_f32_16x16x32_bf16 v[16:19], v[180:183], v[208:211], v[16:19]
	v_mfma_f32_16x16x32_bf16 v[4:7], v[164:167], v[216:219], v[4:7]
	v_mfma_f32_16x16x32_bf16 v[0:3], v[180:183], v[216:219], v[0:3]
	s_setprio 0
	s_barrier
	s_add_i32 s77, 0, 0x18000
	s_add_i32 s78, 0, 0x1c000
	v_add_u32_e32 v100, s77, v173
	v_add_u32_e32 v179, s78, v173
	ds_read_b128 v[88:91], v100
	ds_read_b128 v[92:95], v100 offset:1024
	ds_read_b128 v[96:99], v100 offset:2048
	ds_read_b128 v[100:103], v100 offset:3072
	ds_read_b128 v[160:163], v179
	ds_read_b128 v[164:167], v179 offset:1024
	ds_read_b128 v[168:171], v179 offset:2048
	ds_read_b128 v[180:183], v179 offset:3072
	s_add_u32 s52, s52, 0x40000
	s_addc_u32 s53, s53, 0
	s_mov_b32 m0, s57
	v_lshl_add_u64 v[226:227], s[52:53], 0, v[144:145]
	ds_read_b128 v[184:187], v177 offset:32768
	ds_read_b128 v[188:191], v177 offset:33792
	ds_read_b128 v[192:195], v177 offset:34816
	ds_read_b128 v[200:203], v177 offset:35840
	ds_read_b128 v[204:207], v177 offset:36864
	ds_read_b128 v[208:211], v177 offset:37888
	ds_read_b128 v[212:215], v177 offset:38912
	ds_read_b128 v[216:219], v177 offset:39936
	global_load_lds_dwordx4 v[226:227], off
	v_lshl_add_u64 v[226:227], s[52:53], 0, v[148:149]
	s_mov_b32 m0, s58
	s_nop 0
	global_load_lds_dwordx4 v[226:227], off
	s_waitcnt vmcnt(8)
	s_waitcnt lgkmcnt(0)
	s_barrier
	s_setprio 1
	s_waitcnt lgkmcnt(0)
	v_mfma_f32_16x16x32_bf16 v[140:143], v[88:91], v[184:187], v[140:143]
	v_mfma_f32_16x16x32_bf16 v[136:139], v[96:99], v[184:187], v[136:139]
	v_mfma_f32_16x16x32_bf16 v[124:127], v[88:91], v[192:195], v[124:127]
	v_mfma_f32_16x16x32_bf16 v[120:123], v[96:99], v[192:195], v[120:123]
	v_mfma_f32_16x16x32_bf16 v[108:111], v[88:91], v[204:207], v[108:111]
	v_mfma_f32_16x16x32_bf16 v[104:107], v[96:99], v[204:207], v[104:107]
	v_mfma_f32_16x16x32_bf16 v[76:79], v[88:91], v[212:215], v[76:79]
	v_mfma_f32_16x16x32_bf16 v[72:75], v[96:99], v[212:215], v[72:75]
	v_mfma_f32_16x16x32_bf16 v[140:143], v[92:95], v[188:191], v[140:143]
	v_mfma_f32_16x16x32_bf16 v[136:139], v[100:103], v[188:191], v[136:139]
	v_mfma_f32_16x16x32_bf16 v[124:127], v[92:95], v[200:203], v[124:127]
	v_mfma_f32_16x16x32_bf16 v[120:123], v[100:103], v[200:203], v[120:123]
	v_mfma_f32_16x16x32_bf16 v[108:111], v[92:95], v[208:211], v[108:111]
	v_mfma_f32_16x16x32_bf16 v[104:107], v[100:103], v[208:211], v[104:107]
	v_mfma_f32_16x16x32_bf16 v[76:79], v[92:95], v[216:219], v[76:79]
	v_mfma_f32_16x16x32_bf16 v[72:75], v[100:103], v[216:219], v[72:75]
	v_mfma_f32_16x16x32_bf16 v[132:135], v[160:163], v[184:187], v[132:135]
	v_mfma_f32_16x16x32_bf16 v[128:131], v[168:171], v[184:187], v[128:131]
	v_mfma_f32_16x16x32_bf16 v[116:119], v[160:163], v[192:195], v[116:119]
	v_mfma_f32_16x16x32_bf16 v[112:115], v[168:171], v[192:195], v[112:115]
	v_mfma_f32_16x16x32_bf16 v[84:87], v[160:163], v[204:207], v[84:87]
	v_mfma_f32_16x16x32_bf16 v[80:83], v[168:171], v[204:207], v[80:83]
	v_mfma_f32_16x16x32_bf16 v[68:71], v[160:163], v[212:215], v[68:71]
	v_mfma_f32_16x16x32_bf16 v[64:67], v[168:171], v[212:215], v[64:67]
	v_mfma_f32_16x16x32_bf16 v[132:135], v[164:167], v[188:191], v[132:135]
	v_mfma_f32_16x16x32_bf16 v[128:131], v[180:183], v[188:191], v[128:131]
	v_mfma_f32_16x16x32_bf16 v[116:119], v[164:167], v[200:203], v[116:119]
	v_mfma_f32_16x16x32_bf16 v[112:115], v[180:183], v[200:203], v[112:115]
	v_mfma_f32_16x16x32_bf16 v[84:87], v[164:167], v[208:211], v[84:87]
	v_mfma_f32_16x16x32_bf16 v[80:83], v[180:183], v[208:211], v[80:83]
	v_mfma_f32_16x16x32_bf16 v[68:71], v[164:167], v[216:219], v[68:71]
	v_mfma_f32_16x16x32_bf16 v[64:67], v[180:183], v[216:219], v[64:67]
	s_setprio 0
	s_barrier
	s_add_i32 s52, s77, s55
	v_lshl_add_u64 v[196:197], v[196:197], 0, s[8:9]
	s_mov_b32 m0, s52
	ds_read_b128 v[184:187], v177 offset:49152
	ds_read_b128 v[188:191], v177 offset:50176
	ds_read_b128 v[192:195], v177 offset:51200
	ds_read_b128 v[200:203], v177 offset:52224
	ds_read_b128 v[204:207], v177 offset:53248
	ds_read_b128 v[208:211], v177 offset:54272
	ds_read_b128 v[212:215], v177 offset:55296
	ds_read_b128 v[216:219], v177 offset:56320
	global_load_lds_dwordx4 v[196:197], off
	s_add_i32 m0, s52, 0x2000
	s_add_u32 s50, s50, 0x40080
	v_lshl_add_u64 v[196:197], v[220:221], 0, s[8:9]
	s_addc_u32 s51, s51, 0
	s_add_i32 s52, s78, s55
	global_load_lds_dwordx4 v[196:197], off
	v_lshl_add_u64 v[196:197], s[50:51], 0, v[146:147]
	s_mov_b32 m0, s52
	s_nop 0
	global_load_lds_dwordx4 v[196:197], off
	v_lshl_add_u64 v[196:197], s[50:51], 0, v[150:151]
	s_add_i32 m0, s52, 0x2000
	s_nop 0
	global_load_lds_dwordx4 v[196:197], off
	v_lshl_add_u64 v[196:197], v[222:223], 0, s[8:9]
	s_mov_b32 m0, s61
	s_nop 0
	global_load_lds_dwordx4 v[196:197], off
	v_lshl_add_u64 v[196:197], v[224:225], 0, s[8:9]
	s_mov_b32 m0, s62
	s_nop 0
	global_load_lds_dwordx4 v[196:197], off
	s_add_i32 s76, s76, 2
	s_add_u32 s48, s48, 0x100
	s_addc_u32 s49, s49, 0
	s_add_u32 s45, s45, 0x100
	s_addc_u32 s75, s75, 0
	s_waitcnt vmcnt(8)
	s_waitcnt lgkmcnt(0)
	s_barrier
	s_setprio 1
	s_waitcnt lgkmcnt(0)
	v_mfma_f32_16x16x32_bf16 v[60:63], v[88:91], v[184:187], v[60:63]
	v_mfma_f32_16x16x32_bf16 v[56:59], v[96:99], v[184:187], v[56:59]
	v_mfma_f32_16x16x32_bf16 v[44:47], v[88:91], v[192:195], v[44:47]
	v_mfma_f32_16x16x32_bf16 v[40:43], v[96:99], v[192:195], v[40:43]
	v_mfma_f32_16x16x32_bf16 v[28:31], v[88:91], v[204:207], v[28:31]
	v_mfma_f32_16x16x32_bf16 v[24:27], v[96:99], v[204:207], v[24:27]
	v_mfma_f32_16x16x32_bf16 v[12:15], v[88:91], v[212:215], v[12:15]
	v_mfma_f32_16x16x32_bf16 v[8:11], v[96:99], v[212:215], v[8:11]
	v_mfma_f32_16x16x32_bf16 v[60:63], v[92:95], v[188:191], v[60:63]
	v_mfma_f32_16x16x32_bf16 v[56:59], v[100:103], v[188:191], v[56:59]
	v_mfma_f32_16x16x32_bf16 v[44:47], v[92:95], v[200:203], v[44:47]
	v_mfma_f32_16x16x32_bf16 v[40:43], v[100:103], v[200:203], v[40:43]
	v_mfma_f32_16x16x32_bf16 v[28:31], v[92:95], v[208:211], v[28:31]
	v_mfma_f32_16x16x32_bf16 v[24:27], v[100:103], v[208:211], v[24:27]
	v_mfma_f32_16x16x32_bf16 v[12:15], v[92:95], v[216:219], v[12:15]
	v_mfma_f32_16x16x32_bf16 v[8:11], v[100:103], v[216:219], v[8:11]
	v_mfma_f32_16x16x32_bf16 v[52:55], v[160:163], v[184:187], v[52:55]
	v_mfma_f32_16x16x32_bf16 v[48:51], v[168:171], v[184:187], v[48:51]
	v_mfma_f32_16x16x32_bf16 v[36:39], v[160:163], v[192:195], v[36:39]
	v_mfma_f32_16x16x32_bf16 v[32:35], v[168:171], v[192:195], v[32:35]
	v_mfma_f32_16x16x32_bf16 v[20:23], v[160:163], v[204:207], v[20:23]
	v_mfma_f32_16x16x32_bf16 v[16:19], v[168:171], v[204:207], v[16:19]
	v_mfma_f32_16x16x32_bf16 v[4:7], v[160:163], v[212:215], v[4:7]
	v_mfma_f32_16x16x32_bf16 v[0:3], v[168:171], v[212:215], v[0:3]
	v_mfma_f32_16x16x32_bf16 v[52:55], v[164:167], v[188:191], v[52:55]
	v_mfma_f32_16x16x32_bf16 v[48:51], v[180:183], v[188:191], v[48:51]
	v_mfma_f32_16x16x32_bf16 v[36:39], v[164:167], v[200:203], v[36:39]
	v_mfma_f32_16x16x32_bf16 v[32:35], v[180:183], v[200:203], v[32:35]
	v_mfma_f32_16x16x32_bf16 v[20:23], v[164:167], v[208:211], v[20:23]
	v_mfma_f32_16x16x32_bf16 v[16:19], v[180:183], v[208:211], v[16:19]
	v_mfma_f32_16x16x32_bf16 v[4:7], v[164:167], v[216:219], v[4:7]
	v_mfma_f32_16x16x32_bf16 v[0:3], v[180:183], v[216:219], v[0:3]
	s_setprio 0
	s_barrier
	s_cmp_gt_u32 s76, 13
	s_cbranch_scc0 .LBB0_1576
	s_and_b64 vcc, exec, s[12:13]
	s_cbranch_vccz .LBB0_1579
	s_barrier

.LBB0_1671:
	ds_read_b128 v[64:67], v176
	ds_read_b128 v[68:71], v176 offset:1024
	ds_read_b128 v[76:79], v176 offset:2048
	ds_read_b128 v[80:83], v176 offset:3072
	ds_read_b128 v[184:187], v177
	ds_read_b128 v[188:191], v177 offset:1024
	ds_read_b128 v[192:195], v177 offset:2048
	ds_read_b128 v[200:203], v177 offset:3072
	s_add_u32 s26, s24, 0xfffc0080
	s_addc_u32 s27, s25, -1
	s_cmp_eq_u32 s66, 12
	s_cselect_b32 s43, s1, s27
	s_cselect_b32 s42, s10, s26
	s_cselect_b32 s27, s11, s65
	s_cselect_b32 s26, s17, s19
	v_lshl_add_u64 v[162:163], s[24:25], 0, v[154:155]
	s_add_i32 m0, s49, 0xc000
	ds_read_b128 v[204:207], v178
	ds_read_b128 v[208:211], v178 offset:1024
	ds_read_b128 v[212:215], v178 offset:2048
	ds_read_b128 v[216:219], v178 offset:3072
	ds_read_b128 v[220:223], v178 offset:4096
	ds_read_b128 v[224:227], v178 offset:5120
	ds_read_b128 v[228:231], v178 offset:6144
	ds_read_b128 v[232:235], v178 offset:7168
	global_load_lds_dwordx4 v[162:163], off
	v_lshl_add_u64 v[162:163], s[24:25], 0, v[156:157]
	s_add_i32 m0, s49, 0xe000
	s_nop 0
	global_load_lds_dwordx4 v[162:163], off
	s_waitcnt vmcnt(8)
	s_waitcnt lgkmcnt(0)
	s_barrier
	s_setprio 1
	s_waitcnt lgkmcnt(0)
	v_mfma_f32_16x16x32_bf16 v[140:143], v[64:67], v[204:207], v[140:143]
	v_mfma_f32_16x16x32_bf16 v[132:135], v[76:79], v[204:207], v[132:135]
	v_mfma_f32_16x16x32_bf16 v[124:127], v[64:67], v[212:215], v[124:127]
	v_mfma_f32_16x16x32_bf16 v[120:123], v[76:79], v[212:215], v[120:123]
	v_mfma_f32_16x16x32_bf16 v[108:111], v[64:67], v[220:223], v[108:111]
	v_mfma_f32_16x16x32_bf16 v[104:107], v[76:79], v[220:223], v[104:107]
	v_mfma_f32_16x16x32_bf16 v[92:95], v[64:67], v[228:231], v[92:95]
	v_mfma_f32_16x16x32_bf16 v[88:91], v[76:79], v[228:231], v[88:91]
	v_mfma_f32_16x16x32_bf16 v[140:143], v[68:71], v[208:211], v[140:143]
	v_mfma_f32_16x16x32_bf16 v[132:135], v[80:83], v[208:211], v[132:135]
	v_mfma_f32_16x16x32_bf16 v[124:127], v[68:71], v[216:219], v[124:127]
	v_mfma_f32_16x16x32_bf16 v[120:123], v[80:83], v[216:219], v[120:123]
	v_mfma_f32_16x16x32_bf16 v[108:111], v[68:71], v[224:227], v[108:111]
	v_mfma_f32_16x16x32_bf16 v[104:107], v[80:83], v[224:227], v[104:107]
	v_mfma_f32_16x16x32_bf16 v[92:95], v[68:71], v[232:235], v[92:95]
	v_mfma_f32_16x16x32_bf16 v[88:91], v[80:83], v[232:235], v[88:91]
	v_mfma_f32_16x16x32_bf16 v[136:139], v[184:187], v[204:207], v[136:139]
	v_mfma_f32_16x16x32_bf16 v[128:131], v[192:195], v[204:207], v[128:131]
	v_mfma_f32_16x16x32_bf16 v[116:119], v[184:187], v[212:215], v[116:119]
	v_mfma_f32_16x16x32_bf16 v[112:115], v[192:195], v[212:215], v[112:115]
	v_mfma_f32_16x16x32_bf16 v[100:103], v[184:187], v[220:223], v[100:103]
	v_mfma_f32_16x16x32_bf16 v[96:99], v[192:195], v[220:223], v[96:99]
	v_mfma_f32_16x16x32_bf16 v[84:87], v[184:187], v[228:231], v[84:87]
	v_mfma_f32_16x16x32_bf16 v[72:75], v[192:195], v[228:231], v[72:75]
	v_mfma_f32_16x16x32_bf16 v[136:139], v[188:191], v[208:211], v[136:139]
	v_mfma_f32_16x16x32_bf16 v[128:131], v[200:203], v[208:211], v[128:131]
	v_mfma_f32_16x16x32_bf16 v[116:119], v[188:191], v[216:219], v[116:119]
	v_mfma_f32_16x16x32_bf16 v[112:115], v[200:203], v[216:219], v[112:115]
	v_mfma_f32_16x16x32_bf16 v[100:103], v[188:191], v[224:227], v[100:103]
	v_mfma_f32_16x16x32_bf16 v[96:99], v[200:203], v[224:227], v[96:99]
	v_mfma_f32_16x16x32_bf16 v[84:87], v[188:191], v[232:235], v[84:87]
	v_mfma_f32_16x16x32_bf16 v[72:75], v[200:203], v[232:235], v[72:75]
	s_setprio 0
	s_barrier
	s_add_i32 s67, s58, s48
	v_lshl_add_u64 v[162:163], s[26:27], 0, v[146:147]
	s_mov_b32 m0, s67
	ds_read_b128 v[204:207], v178 offset:16384
	ds_read_b128 v[208:211], v178 offset:17408
	ds_read_b128 v[212:215], v178 offset:18432
	ds_read_b128 v[216:219], v178 offset:19456
	ds_read_b128 v[220:223], v178 offset:20480
	ds_read_b128 v[224:227], v178 offset:21504
	ds_read_b128 v[228:231], v178 offset:22528
	ds_read_b128 v[232:235], v178 offset:23552
	global_load_lds_dwordx4 v[162:163], off
	s_add_i32 m0, s67, 0x2000
	s_add_u32 s70, s26, 0x40000
	v_lshl_add_u64 v[196:197], s[26:27], 0, v[150:151]
	s_addc_u32 s71, s27, 0
	s_add_i32 s67, s59, s48
	global_load_lds_dwordx4 v[196:197], off
	v_lshl_add_u64 v[236:237], s[70:71], 0, v[146:147]
	s_mov_b32 m0, s67
	v_lshl_add_u64 v[238:239], s[42:43], 0, v[148:149]
	global_load_lds_dwordx4 v[236:237], off
	v_lshl_add_u64 v[236:237], s[70:71], 0, v[150:151]
	s_add_i32 m0, s67, 0x2000
	s_nop 0
	global_load_lds_dwordx4 v[236:237], off
	v_lshl_add_u64 v[236:237], s[42:43], 0, v[144:145]
	s_mov_b32 m0, s49
	s_nop 0
	global_load_lds_dwordx4 v[236:237], off
	s_mov_b32 m0, s50
	s_nop 0
	global_load_lds_dwordx4 v[238:239], off
	s_waitcnt vmcnt(8)
	s_waitcnt lgkmcnt(0)
	s_barrier
	s_setprio 1
	s_waitcnt lgkmcnt(0)
	v_mfma_f32_16x16x32_bf16 v[60:63], v[64:67], v[204:207], v[60:63]
	v_mfma_f32_16x16x32_bf16 v[56:59], v[76:79], v[204:207], v[56:59]
	v_mfma_f32_16x16x32_bf16 v[44:47], v[64:67], v[212:215], v[44:47]
	v_mfma_f32_16x16x32_bf16 v[40:43], v[76:79], v[212:215], v[40:43]
	v_mfma_f32_16x16x32_bf16 v[28:31], v[64:67], v[220:223], v[28:31]
	v_mfma_f32_16x16x32_bf16 v[24:27], v[76:79], v[220:223], v[24:27]
	v_mfma_f32_16x16x32_bf16 v[12:15], v[64:67], v[228:231], v[12:15]
	v_mfma_f32_16x16x32_bf16 v[8:11], v[76:79], v[228:231], v[8:11]
	v_mfma_f32_16x16x32_bf16 v[60:63], v[68:71], v[208:211], v[60:63]
	v_mfma_f32_16x16x32_bf16 v[56:59], v[80:83], v[208:211], v[56:59]
	v_mfma_f32_16x16x32_bf16 v[44:47], v[68:71], v[216:219], v[44:47]
	v_mfma_f32_16x16x32_bf16 v[40:43], v[80:83], v[216:219], v[40:43]
	v_mfma_f32_16x16x32_bf16 v[28:31], v[68:71], v[224:227], v[28:31]
	v_mfma_f32_16x16x32_bf16 v[24:27], v[80:83], v[224:227], v[24:27]
	v_mfma_f32_16x16x32_bf16 v[12:15], v[68:71], v[232:235], v[12:15]
	v_mfma_f32_16x16x32_bf16 v[8:11], v[80:83], v[232:235], v[8:11]
	v_mfma_f32_16x16x32_bf16 v[52:55], v[184:187], v[204:207], v[52:55]
	v_mfma_f32_16x16x32_bf16 v[48:51], v[192:195], v[204:207], v[48:51]
	v_mfma_f32_16x16x32_bf16 v[36:39], v[184:187], v[212:215], v[36:39]
	v_mfma_f32_16x16x32_bf16 v[32:35], v[192:195], v[212:215], v[32:35]
	v_mfma_f32_16x16x32_bf16 v[20:23], v[184:187], v[220:223], v[20:23]
	v_mfma_f32_16x16x32_bf16 v[16:19], v[192:195], v[220:223], v[16:19]
	v_mfma_f32_16x16x32_bf16 v[4:7], v[184:187], v[228:231], v[4:7]
	v_mfma_f32_16x16x32_bf16 v[0:3], v[192:195], v[228:231], v[0:3]
	v_mfma_f32_16x16x32_bf16 v[52:55], v[188:191], v[208:211], v[52:55]
	v_mfma_f32_16x16x32_bf16 v[48:51], v[200:203], v[208:211], v[48:51]
	v_mfma_f32_16x16x32_bf16 v[36:39], v[188:191], v[216:219], v[36:39]
	v_mfma_f32_16x16x32_bf16 v[32:35], v[200:203], v[216:219], v[32:35]
	v_mfma_f32_16x16x32_bf16 v[20:23], v[188:191], v[224:227], v[20:23]
	v_mfma_f32_16x16x32_bf16 v[16:19], v[200:203], v[224:227], v[16:19]
	v_mfma_f32_16x16x32_bf16 v[4:7], v[188:191], v[232:235], v[4:7]
	v_mfma_f32_16x16x32_bf16 v[0:3], v[200:203], v[232:235], v[0:3]
	s_setprio 0
	s_barrier
	s_add_i32 s67, 0, 0x18000
	s_add_i32 s70, 0, 0x1c000
	v_add_u32_e32 v80, s67, v166
	v_add_u32_e32 v164, s70, v166
	ds_read_b128 v[64:67], v80
	ds_read_b128 v[68:71], v80 offset:1024
	ds_read_b128 v[76:79], v80 offset:2048
	ds_read_b128 v[80:83], v80 offset:3072
	ds_read_b128 v[184:187], v164
	ds_read_b128 v[188:191], v164 offset:1024
	ds_read_b128 v[192:195], v164 offset:2048
	ds_read_b128 v[200:203], v164 offset:3072
	s_add_u32 s42, s42, 0x40000
	s_addc_u32 s43, s43, 0
	s_mov_b32 m0, s51
	v_lshl_add_u64 v[240:241], s[42:43], 0, v[144:145]
	ds_read_b128 v[204:207], v178 offset:32768
	ds_read_b128 v[208:211], v178 offset:33792
	ds_read_b128 v[212:215], v178 offset:34816
	ds_read_b128 v[216:219], v178 offset:35840
	ds_read_b128 v[220:223], v178 offset:36864
	ds_read_b128 v[224:227], v178 offset:37888
	ds_read_b128 v[228:231], v178 offset:38912
	ds_read_b128 v[232:235], v178 offset:39936
	global_load_lds_dwordx4 v[240:241], off
	v_lshl_add_u64 v[240:241], s[42:43], 0, v[148:149]
	s_mov_b32 m0, s52
	s_nop 0
	global_load_lds_dwordx4 v[240:241], off
	s_waitcnt vmcnt(8)
	s_waitcnt lgkmcnt(0)
	s_barrier
	s_setprio 1
	s_waitcnt lgkmcnt(0)
	v_mfma_f32_16x16x32_bf16 v[140:143], v[64:67], v[204:207], v[140:143]
	v_mfma_f32_16x16x32_bf16 v[132:135], v[76:79], v[204:207], v[132:135]
	v_mfma_f32_16x16x32_bf16 v[124:127], v[64:67], v[212:215], v[124:127]
	v_mfma_f32_16x16x32_bf16 v[120:123], v[76:79], v[212:215], v[120:123]
	v_mfma_f32_16x16x32_bf16 v[108:111], v[64:67], v[220:223], v[108:111]
	v_mfma_f32_16x16x32_bf16 v[104:107], v[76:79], v[220:223], v[104:107]
	v_mfma_f32_16x16x32_bf16 v[92:95], v[64:67], v[228:231], v[92:95]
	v_mfma_f32_16x16x32_bf16 v[88:91], v[76:79], v[228:231], v[88:91]
	v_mfma_f32_16x16x32_bf16 v[140:143], v[68:71], v[208:211], v[140:143]
	v_mfma_f32_16x16x32_bf16 v[132:135], v[80:83], v[208:211], v[132:135]
	v_mfma_f32_16x16x32_bf16 v[124:127], v[68:71], v[216:219], v[124:127]
	v_mfma_f32_16x16x32_bf16 v[120:123], v[80:83], v[216:219], v[120:123]
	v_mfma_f32_16x16x32_bf16 v[108:111], v[68:71], v[224:227], v[108:111]
	v_mfma_f32_16x16x32_bf16 v[104:107], v[80:83], v[224:227], v[104:107]
	v_mfma_f32_16x16x32_bf16 v[92:95], v[68:71], v[232:235], v[92:95]
	v_mfma_f32_16x16x32_bf16 v[88:91], v[80:83], v[232:235], v[88:91]
	v_mfma_f32_16x16x32_bf16 v[136:139], v[184:187], v[204:207], v[136:139]
	v_mfma_f32_16x16x32_bf16 v[128:131], v[192:195], v[204:207], v[128:131]
	v_mfma_f32_16x16x32_bf16 v[116:119], v[184:187], v[212:215], v[116:119]
	v_mfma_f32_16x16x32_bf16 v[112:115], v[192:195], v[212:215], v[112:115]
	v_mfma_f32_16x16x32_bf16 v[100:103], v[184:187], v[220:223], v[100:103]
	v_mfma_f32_16x16x32_bf16 v[96:99], v[192:195], v[220:223], v[96:99]
	v_mfma_f32_16x16x32_bf16 v[84:87], v[184:187], v[228:231], v[84:87]
	v_mfma_f32_16x16x32_bf16 v[72:75], v[192:195], v[228:231], v[72:75]
	v_mfma_f32_16x16x32_bf16 v[136:139], v[188:191], v[208:211], v[136:139]
	v_mfma_f32_16x16x32_bf16 v[128:131], v[200:203], v[208:211], v[128:131]
	v_mfma_f32_16x16x32_bf16 v[116:119], v[188:191], v[216:219], v[116:119]
	v_mfma_f32_16x16x32_bf16 v[112:115], v[200:203], v[216:219], v[112:115]
	v_mfma_f32_16x16x32_bf16 v[100:103], v[188:191], v[224:227], v[100:103]
	v_mfma_f32_16x16x32_bf16 v[96:99], v[200:203], v[224:227], v[96:99]
	v_mfma_f32_16x16x32_bf16 v[84:87], v[188:191], v[232:235], v[84:87]
	v_mfma_f32_16x16x32_bf16 v[72:75], v[200:203], v[232:235], v[72:75]
	s_setprio 0
	s_barrier
	s_add_i32 s42, s67, s48
	v_lshl_add_u64 v[162:163], v[162:163], 0, s[12:13]
	s_mov_b32 m0, s42
	ds_read_b128 v[204:207], v178 offset:49152
	ds_read_b128 v[208:211], v178 offset:50176
	ds_read_b128 v[212:215], v178 offset:51200
	ds_read_b128 v[216:219], v178 offset:52224
	ds_read_b128 v[220:223], v178 offset:53248
	ds_read_b128 v[224:227], v178 offset:54272
	ds_read_b128 v[228:231], v178 offset:55296
	ds_read_b128 v[232:235], v178 offset:56320
	global_load_lds_dwordx4 v[162:163], off
	s_add_i32 m0, s42, 0x2000
	s_add_u32 s26, s26, 0x40080
	v_lshl_add_u64 v[162:163], v[196:197], 0, s[12:13]
	s_addc_u32 s27, s27, 0
	s_add_i32 s42, s70, s48
	global_load_lds_dwordx4 v[162:163], off
	v_lshl_add_u64 v[162:163], s[26:27], 0, v[146:147]
	s_mov_b32 m0, s42
	s_nop 0
	global_load_lds_dwordx4 v[162:163], off
	v_lshl_add_u64 v[162:163], s[26:27], 0, v[150:151]
	s_add_i32 m0, s42, 0x2000
	s_nop 0
	global_load_lds_dwordx4 v[162:163], off
	v_lshl_add_u64 v[162:163], v[236:237], 0, s[12:13]
	s_mov_b32 m0, s55
	s_nop 0
	global_load_lds_dwordx4 v[162:163], off
	v_lshl_add_u64 v[162:163], v[238:239], 0, s[12:13]
	s_mov_b32 m0, s56
	s_nop 0
	global_load_lds_dwordx4 v[162:163], off
	s_add_i32 s66, s66, 2
	s_add_u32 s24, s24, 0x100
	s_addc_u32 s25, s25, 0
	s_add_u32 s19, s19, 0x100
	s_addc_u32 s65, s65, 0
	s_waitcnt vmcnt(8)
	s_waitcnt lgkmcnt(0)
	s_barrier
	s_setprio 1
	s_waitcnt lgkmcnt(0)
	v_mfma_f32_16x16x32_bf16 v[60:63], v[64:67], v[204:207], v[60:63]
	v_mfma_f32_16x16x32_bf16 v[56:59], v[76:79], v[204:207], v[56:59]
	v_mfma_f32_16x16x32_bf16 v[44:47], v[64:67], v[212:215], v[44:47]
	v_mfma_f32_16x16x32_bf16 v[40:43], v[76:79], v[212:215], v[40:43]
	v_mfma_f32_16x16x32_bf16 v[28:31], v[64:67], v[220:223], v[28:31]
	v_mfma_f32_16x16x32_bf16 v[24:27], v[76:79], v[220:223], v[24:27]
	v_mfma_f32_16x16x32_bf16 v[12:15], v[64:67], v[228:231], v[12:15]
	v_mfma_f32_16x16x32_bf16 v[8:11], v[76:79], v[228:231], v[8:11]
	v_mfma_f32_16x16x32_bf16 v[60:63], v[68:71], v[208:211], v[60:63]
	v_mfma_f32_16x16x32_bf16 v[56:59], v[80:83], v[208:211], v[56:59]
	v_mfma_f32_16x16x32_bf16 v[44:47], v[68:71], v[216:219], v[44:47]
	v_mfma_f32_16x16x32_bf16 v[40:43], v[80:83], v[216:219], v[40:43]
	v_mfma_f32_16x16x32_bf16 v[28:31], v[68:71], v[224:227], v[28:31]
	v_mfma_f32_16x16x32_bf16 v[24:27], v[80:83], v[224:227], v[24:27]
	v_mfma_f32_16x16x32_bf16 v[12:15], v[68:71], v[232:235], v[12:15]
	v_mfma_f32_16x16x32_bf16 v[8:11], v[80:83], v[232:235], v[8:11]
	v_mfma_f32_16x16x32_bf16 v[52:55], v[184:187], v[204:207], v[52:55]
	v_mfma_f32_16x16x32_bf16 v[48:51], v[192:195], v[204:207], v[48:51]
	v_mfma_f32_16x16x32_bf16 v[36:39], v[184:187], v[212:215], v[36:39]
	v_mfma_f32_16x16x32_bf16 v[32:35], v[192:195], v[212:215], v[32:35]
	v_mfma_f32_16x16x32_bf16 v[20:23], v[184:187], v[220:223], v[20:23]
	v_mfma_f32_16x16x32_bf16 v[16:19], v[192:195], v[220:223], v[16:19]
	v_mfma_f32_16x16x32_bf16 v[4:7], v[184:187], v[228:231], v[4:7]
	v_mfma_f32_16x16x32_bf16 v[0:3], v[192:195], v[228:231], v[0:3]
	v_mfma_f32_16x16x32_bf16 v[52:55], v[188:191], v[208:211], v[52:55]
	v_mfma_f32_16x16x32_bf16 v[48:51], v[200:203], v[208:211], v[48:51]
	v_mfma_f32_16x16x32_bf16 v[36:39], v[188:191], v[216:219], v[36:39]
	v_mfma_f32_16x16x32_bf16 v[32:35], v[200:203], v[216:219], v[32:35]
	v_mfma_f32_16x16x32_bf16 v[20:23], v[188:191], v[224:227], v[20:23]
	v_mfma_f32_16x16x32_bf16 v[16:19], v[200:203], v[224:227], v[16:19]
	v_mfma_f32_16x16x32_bf16 v[4:7], v[188:191], v[232:235], v[4:7]
	v_mfma_f32_16x16x32_bf16 v[0:3], v[200:203], v[232:235], v[0:3]
	s_setprio 0
	s_barrier
	s_cmp_gt_u32 s66, 13
	s_cbranch_scc0 .LBB0_1671
	s_and_b64 vcc, exec, s[14:15]
	s_cbranch_vccz .LBB0_1674
	s_barrier

.LBB0_1786:
	ds_read_b128 v[144:147], v167
	ds_read_b128 v[148:151], v167 offset:1024
	ds_read_b128 v[152:155], v167 offset:2048
	ds_read_b128 v[156:159], v167 offset:3072
	ds_read_b128 v[160:163], v168
	ds_read_b128 v[170:173], v168 offset:1024
	ds_read_b128 v[174:177], v168 offset:2048
	ds_read_b128 v[178:181], v168 offset:3072
	s_add_u32 s16, s14, 0xfff50080
	s_addc_u32 s17, s15, -1
	s_cmp_eq_u32 s50, 40
	s_cselect_b32 s19, s3, s17
	s_cselect_b32 s18, s2, s16
	s_cselect_b32 s17, s13, s49
	s_cselect_b32 s16, s12, s48
	v_lshl_add_u64 v[214:215], s[14:15], 0, v[136:137]
	s_add_i32 m0, s24, 0xc000
	ds_read_b128 v[182:185], v169
	ds_read_b128 v[186:189], v169 offset:1024
	ds_read_b128 v[190:193], v169 offset:2048
	ds_read_b128 v[194:197], v169 offset:3072
	ds_read_b128 v[198:201], v169 offset:4096
	ds_read_b128 v[202:205], v169 offset:5120
	ds_read_b128 v[206:209], v169 offset:6144
	ds_read_b128 v[210:213], v169 offset:7168
	global_load_lds_dwordx4 v[214:215], off
	v_lshl_add_u64 v[214:215], s[14:15], 0, v[138:139]
	s_add_i32 m0, s24, 0xe000
	s_nop 0
	global_load_lds_dwordx4 v[214:215], off
	s_waitcnt vmcnt(8)
	s_waitcnt lgkmcnt(0)
	s_barrier
	s_setprio 1
	s_waitcnt lgkmcnt(0)
	v_mfma_f32_16x16x32_bf16 v[124:127], v[144:147], v[182:185], v[124:127]
	v_mfma_f32_16x16x32_bf16 v[120:123], v[152:155], v[182:185], v[120:123]
	v_mfma_f32_16x16x32_bf16 v[108:111], v[144:147], v[190:193], v[108:111]
	v_mfma_f32_16x16x32_bf16 v[104:107], v[152:155], v[190:193], v[104:107]
	v_mfma_f32_16x16x32_bf16 v[92:95], v[144:147], v[198:201], v[92:95]
	v_mfma_f32_16x16x32_bf16 v[88:91], v[152:155], v[198:201], v[88:91]
	v_mfma_f32_16x16x32_bf16 v[76:79], v[144:147], v[206:209], v[76:79]
	v_mfma_f32_16x16x32_bf16 v[72:75], v[152:155], v[206:209], v[72:75]
	v_mfma_f32_16x16x32_bf16 v[124:127], v[148:151], v[186:189], v[124:127]
	v_mfma_f32_16x16x32_bf16 v[120:123], v[156:159], v[186:189], v[120:123]
	v_mfma_f32_16x16x32_bf16 v[108:111], v[148:151], v[194:197], v[108:111]
	v_mfma_f32_16x16x32_bf16 v[104:107], v[156:159], v[194:197], v[104:107]
	v_mfma_f32_16x16x32_bf16 v[92:95], v[148:151], v[202:205], v[92:95]
	v_mfma_f32_16x16x32_bf16 v[88:91], v[156:159], v[202:205], v[88:91]
	v_mfma_f32_16x16x32_bf16 v[76:79], v[148:151], v[210:213], v[76:79]
	v_mfma_f32_16x16x32_bf16 v[72:75], v[156:159], v[210:213], v[72:75]
	v_mfma_f32_16x16x32_bf16 v[116:119], v[160:163], v[182:185], v[116:119]
	v_mfma_f32_16x16x32_bf16 v[112:115], v[174:177], v[182:185], v[112:115]
	v_mfma_f32_16x16x32_bf16 v[100:103], v[160:163], v[190:193], v[100:103]
	v_mfma_f32_16x16x32_bf16 v[96:99], v[174:177], v[190:193], v[96:99]
	v_mfma_f32_16x16x32_bf16 v[84:87], v[160:163], v[198:201], v[84:87]
	v_mfma_f32_16x16x32_bf16 v[80:83], v[174:177], v[198:201], v[80:83]
	v_mfma_f32_16x16x32_bf16 v[68:71], v[160:163], v[206:209], v[68:71]
	v_mfma_f32_16x16x32_bf16 v[64:67], v[174:177], v[206:209], v[64:67]
	v_mfma_f32_16x16x32_bf16 v[116:119], v[170:173], v[186:189], v[116:119]
	v_mfma_f32_16x16x32_bf16 v[112:115], v[178:181], v[186:189], v[112:115]
	v_mfma_f32_16x16x32_bf16 v[100:103], v[170:173], v[194:197], v[100:103]
	v_mfma_f32_16x16x32_bf16 v[96:99], v[178:181], v[194:197], v[96:99]
	v_mfma_f32_16x16x32_bf16 v[84:87], v[170:173], v[202:205], v[84:87]
	v_mfma_f32_16x16x32_bf16 v[80:83], v[178:181], v[202:205], v[80:83]
	v_mfma_f32_16x16x32_bf16 v[68:71], v[170:173], v[210:213], v[68:71]
	v_mfma_f32_16x16x32_bf16 v[64:67], v[178:181], v[210:213], v[64:67]
	s_setprio 0
	s_barrier
	s_add_i32 s51, s41, s23
	v_lshl_add_u64 v[214:215], s[16:17], 0, v[130:131]
	s_mov_b32 m0, s51
	ds_read_b128 v[182:185], v169 offset:16384
	ds_read_b128 v[186:189], v169 offset:17408
	ds_read_b128 v[190:193], v169 offset:18432
	ds_read_b128 v[194:197], v169 offset:19456
	ds_read_b128 v[198:201], v169 offset:20480
	ds_read_b128 v[202:205], v169 offset:21504
	ds_read_b128 v[206:209], v169 offset:22528
	ds_read_b128 v[210:213], v169 offset:23552
	global_load_lds_dwordx4 v[214:215], off
	s_add_i32 m0, s51, 0x2000
	s_add_u32 s52, s16, 0xb0000
	v_lshl_add_u64 v[216:217], s[16:17], 0, v[134:135]
	s_addc_u32 s53, s17, 0
	s_add_i32 s51, s42, s23
	global_load_lds_dwordx4 v[216:217], off
	v_lshl_add_u64 v[218:219], s[52:53], 0, v[130:131]
	s_mov_b32 m0, s51
	v_lshl_add_u64 v[220:221], s[18:19], 0, v[132:133]
	global_load_lds_dwordx4 v[218:219], off
	v_lshl_add_u64 v[218:219], s[52:53], 0, v[134:135]
	s_add_i32 m0, s51, 0x2000
	s_nop 0
	global_load_lds_dwordx4 v[218:219], off
	v_lshl_add_u64 v[218:219], s[18:19], 0, v[128:129]
	s_mov_b32 m0, s24
	s_nop 0
	global_load_lds_dwordx4 v[218:219], off
	s_mov_b32 m0, s25
	s_nop 0
	global_load_lds_dwordx4 v[220:221], off
	s_waitcnt vmcnt(8)
	s_waitcnt lgkmcnt(0)
	s_barrier
	s_setprio 1
	s_waitcnt lgkmcnt(0)
	v_mfma_f32_16x16x32_bf16 v[60:63], v[144:147], v[182:185], v[60:63]
	v_mfma_f32_16x16x32_bf16 v[56:59], v[152:155], v[182:185], v[56:59]
	v_mfma_f32_16x16x32_bf16 v[44:47], v[144:147], v[190:193], v[44:47]
	v_mfma_f32_16x16x32_bf16 v[40:43], v[152:155], v[190:193], v[40:43]
	v_mfma_f32_16x16x32_bf16 v[28:31], v[144:147], v[198:201], v[28:31]
	v_mfma_f32_16x16x32_bf16 v[24:27], v[152:155], v[198:201], v[24:27]
	v_mfma_f32_16x16x32_bf16 v[12:15], v[144:147], v[206:209], v[12:15]
	v_mfma_f32_16x16x32_bf16 v[8:11], v[152:155], v[206:209], v[8:11]
	v_mfma_f32_16x16x32_bf16 v[60:63], v[148:151], v[186:189], v[60:63]
	v_mfma_f32_16x16x32_bf16 v[56:59], v[156:159], v[186:189], v[56:59]
	v_mfma_f32_16x16x32_bf16 v[44:47], v[148:151], v[194:197], v[44:47]
	v_mfma_f32_16x16x32_bf16 v[40:43], v[156:159], v[194:197], v[40:43]
	v_mfma_f32_16x16x32_bf16 v[28:31], v[148:151], v[202:205], v[28:31]
	v_mfma_f32_16x16x32_bf16 v[24:27], v[156:159], v[202:205], v[24:27]
	v_mfma_f32_16x16x32_bf16 v[12:15], v[148:151], v[210:213], v[12:15]
	v_mfma_f32_16x16x32_bf16 v[8:11], v[156:159], v[210:213], v[8:11]
	v_mfma_f32_16x16x32_bf16 v[52:55], v[160:163], v[182:185], v[52:55]
	v_mfma_f32_16x16x32_bf16 v[48:51], v[174:177], v[182:185], v[48:51]
	v_mfma_f32_16x16x32_bf16 v[36:39], v[160:163], v[190:193], v[36:39]
	v_mfma_f32_16x16x32_bf16 v[32:35], v[174:177], v[190:193], v[32:35]
	v_mfma_f32_16x16x32_bf16 v[20:23], v[160:163], v[198:201], v[20:23]
	v_mfma_f32_16x16x32_bf16 v[16:19], v[174:177], v[198:201], v[16:19]
	v_mfma_f32_16x16x32_bf16 v[4:7], v[160:163], v[206:209], v[4:7]
	v_mfma_f32_16x16x32_bf16 v[0:3], v[174:177], v[206:209], v[0:3]
	v_mfma_f32_16x16x32_bf16 v[52:55], v[170:173], v[186:189], v[52:55]
	v_mfma_f32_16x16x32_bf16 v[48:51], v[178:181], v[186:189], v[48:51]
	v_mfma_f32_16x16x32_bf16 v[36:39], v[170:173], v[194:197], v[36:39]
	v_mfma_f32_16x16x32_bf16 v[32:35], v[178:181], v[194:197], v[32:35]
	v_mfma_f32_16x16x32_bf16 v[20:23], v[170:173], v[202:205], v[20:23]
	v_mfma_f32_16x16x32_bf16 v[16:19], v[178:181], v[202:205], v[16:19]
	v_mfma_f32_16x16x32_bf16 v[4:7], v[170:173], v[210:213], v[4:7]
	v_mfma_f32_16x16x32_bf16 v[0:3], v[178:181], v[210:213], v[0:3]
	s_setprio 0
	s_barrier
	s_add_i32 s51, 0, 0x18000
	s_add_i32 s52, 0, 0x1c000
	v_add_u32_e32 v156, s51, v165
	v_add_u32_e32 v178, s52, v165
	ds_read_b128 v[144:147], v156
	ds_read_b128 v[148:151], v156 offset:1024
	ds_read_b128 v[152:155], v156 offset:2048
	ds_read_b128 v[156:159], v156 offset:3072
	ds_read_b128 v[160:163], v178
	ds_read_b128 v[170:173], v178 offset:1024
	ds_read_b128 v[174:177], v178 offset:2048
	ds_read_b128 v[178:181], v178 offset:3072
	s_add_u32 s18, s18, 0xb0000
	s_addc_u32 s19, s19, 0
	s_mov_b32 m0, s26
	v_lshl_add_u64 v[222:223], s[18:19], 0, v[128:129]
	ds_read_b128 v[182:185], v169 offset:32768
	ds_read_b128 v[186:189], v169 offset:33792
	ds_read_b128 v[190:193], v169 offset:34816
	ds_read_b128 v[194:197], v169 offset:35840
	ds_read_b128 v[198:201], v169 offset:36864
	ds_read_b128 v[202:205], v169 offset:37888
	ds_read_b128 v[206:209], v169 offset:38912
	ds_read_b128 v[210:213], v169 offset:39936
	global_load_lds_dwordx4 v[222:223], off
	v_lshl_add_u64 v[222:223], s[18:19], 0, v[132:133]
	s_mov_b32 m0, s27
	s_nop 0
	global_load_lds_dwordx4 v[222:223], off
	s_waitcnt vmcnt(8)
	s_waitcnt lgkmcnt(0)
	s_barrier
	s_setprio 1
	s_waitcnt lgkmcnt(0)
	v_mfma_f32_16x16x32_bf16 v[124:127], v[144:147], v[182:185], v[124:127]
	v_mfma_f32_16x16x32_bf16 v[120:123], v[152:155], v[182:185], v[120:123]
	v_mfma_f32_16x16x32_bf16 v[108:111], v[144:147], v[190:193], v[108:111]
	v_mfma_f32_16x16x32_bf16 v[104:107], v[152:155], v[190:193], v[104:107]
	v_mfma_f32_16x16x32_bf16 v[92:95], v[144:147], v[198:201], v[92:95]
	v_mfma_f32_16x16x32_bf16 v[88:91], v[152:155], v[198:201], v[88:91]
	v_mfma_f32_16x16x32_bf16 v[76:79], v[144:147], v[206:209], v[76:79]
	v_mfma_f32_16x16x32_bf16 v[72:75], v[152:155], v[206:209], v[72:75]
	v_mfma_f32_16x16x32_bf16 v[124:127], v[148:151], v[186:189], v[124:127]
	v_mfma_f32_16x16x32_bf16 v[120:123], v[156:159], v[186:189], v[120:123]
	v_mfma_f32_16x16x32_bf16 v[108:111], v[148:151], v[194:197], v[108:111]
	v_mfma_f32_16x16x32_bf16 v[104:107], v[156:159], v[194:197], v[104:107]
	v_mfma_f32_16x16x32_bf16 v[92:95], v[148:151], v[202:205], v[92:95]
	v_mfma_f32_16x16x32_bf16 v[88:91], v[156:159], v[202:205], v[88:91]
	v_mfma_f32_16x16x32_bf16 v[76:79], v[148:151], v[210:213], v[76:79]
	v_mfma_f32_16x16x32_bf16 v[72:75], v[156:159], v[210:213], v[72:75]
	v_mfma_f32_16x16x32_bf16 v[116:119], v[160:163], v[182:185], v[116:119]
	v_mfma_f32_16x16x32_bf16 v[112:115], v[174:177], v[182:185], v[112:115]
	v_mfma_f32_16x16x32_bf16 v[100:103], v[160:163], v[190:193], v[100:103]
	v_mfma_f32_16x16x32_bf16 v[96:99], v[174:177], v[190:193], v[96:99]
	v_mfma_f32_16x16x32_bf16 v[84:87], v[160:163], v[198:201], v[84:87]
	v_mfma_f32_16x16x32_bf16 v[80:83], v[174:177], v[198:201], v[80:83]
	v_mfma_f32_16x16x32_bf16 v[68:71], v[160:163], v[206:209], v[68:71]
	v_mfma_f32_16x16x32_bf16 v[64:67], v[174:177], v[206:209], v[64:67]
	v_mfma_f32_16x16x32_bf16 v[116:119], v[170:173], v[186:189], v[116:119]
	v_mfma_f32_16x16x32_bf16 v[112:115], v[178:181], v[186:189], v[112:115]
	v_mfma_f32_16x16x32_bf16 v[100:103], v[170:173], v[194:197], v[100:103]
	v_mfma_f32_16x16x32_bf16 v[96:99], v[178:181], v[194:197], v[96:99]
	v_mfma_f32_16x16x32_bf16 v[84:87], v[170:173], v[202:205], v[84:87]
	v_mfma_f32_16x16x32_bf16 v[80:83], v[178:181], v[202:205], v[80:83]
	v_mfma_f32_16x16x32_bf16 v[68:71], v[170:173], v[210:213], v[68:71]
	v_mfma_f32_16x16x32_bf16 v[64:67], v[178:181], v[210:213], v[64:67]
	s_setprio 0
	s_barrier
	s_add_i32 s18, s51, s23
	v_lshl_add_u64 v[214:215], v[214:215], 0, s[6:7]
	s_mov_b32 m0, s18
	ds_read_b128 v[182:185], v169 offset:49152
	ds_read_b128 v[186:189], v169 offset:50176
	ds_read_b128 v[190:193], v169 offset:51200
	ds_read_b128 v[194:197], v169 offset:52224
	ds_read_b128 v[198:201], v169 offset:53248
	ds_read_b128 v[202:205], v169 offset:54272
	ds_read_b128 v[206:209], v169 offset:55296
	ds_read_b128 v[210:213], v169 offset:56320
	global_load_lds_dwordx4 v[214:215], off
	s_add_i32 m0, s18, 0x2000
	s_add_u32 s16, s16, 0xb0080
	v_lshl_add_u64 v[214:215], v[216:217], 0, s[6:7]
	s_addc_u32 s17, s17, 0
	s_add_i32 s18, s52, s23
	global_load_lds_dwordx4 v[214:215], off
	v_lshl_add_u64 v[214:215], s[16:17], 0, v[130:131]
	s_mov_b32 m0, s18
	s_nop 0
	global_load_lds_dwordx4 v[214:215], off
	v_lshl_add_u64 v[214:215], s[16:17], 0, v[134:135]
	s_add_i32 m0, s18, 0x2000
	s_nop 0
	global_load_lds_dwordx4 v[214:215], off
	v_lshl_add_u64 v[214:215], v[218:219], 0, s[6:7]
	s_mov_b32 m0, s35
	s_nop 0
	global_load_lds_dwordx4 v[214:215], off
	v_lshl_add_u64 v[214:215], v[220:221], 0, s[6:7]
	s_mov_b32 m0, s39
	s_nop 0
	global_load_lds_dwordx4 v[214:215], off
	s_add_i32 s50, s50, 2
	s_add_u32 s14, s14, 0x100
	s_addc_u32 s15, s15, 0
	s_add_u32 s48, s48, 0x100
	s_addc_u32 s49, s49, 0
	s_waitcnt vmcnt(8)
	s_waitcnt lgkmcnt(0)
	s_barrier
	s_setprio 1
	s_waitcnt lgkmcnt(0)
	v_mfma_f32_16x16x32_bf16 v[60:63], v[144:147], v[182:185], v[60:63]
	v_mfma_f32_16x16x32_bf16 v[56:59], v[152:155], v[182:185], v[56:59]
	v_mfma_f32_16x16x32_bf16 v[44:47], v[144:147], v[190:193], v[44:47]
	v_mfma_f32_16x16x32_bf16 v[40:43], v[152:155], v[190:193], v[40:43]
	v_mfma_f32_16x16x32_bf16 v[28:31], v[144:147], v[198:201], v[28:31]
	v_mfma_f32_16x16x32_bf16 v[24:27], v[152:155], v[198:201], v[24:27]
	v_mfma_f32_16x16x32_bf16 v[12:15], v[144:147], v[206:209], v[12:15]
	v_mfma_f32_16x16x32_bf16 v[8:11], v[152:155], v[206:209], v[8:11]
	v_mfma_f32_16x16x32_bf16 v[60:63], v[148:151], v[186:189], v[60:63]
	v_mfma_f32_16x16x32_bf16 v[56:59], v[156:159], v[186:189], v[56:59]
	v_mfma_f32_16x16x32_bf16 v[44:47], v[148:151], v[194:197], v[44:47]
	v_mfma_f32_16x16x32_bf16 v[40:43], v[156:159], v[194:197], v[40:43]
	v_mfma_f32_16x16x32_bf16 v[28:31], v[148:151], v[202:205], v[28:31]
	v_mfma_f32_16x16x32_bf16 v[24:27], v[156:159], v[202:205], v[24:27]
	v_mfma_f32_16x16x32_bf16 v[12:15], v[148:151], v[210:213], v[12:15]
	v_mfma_f32_16x16x32_bf16 v[8:11], v[156:159], v[210:213], v[8:11]
	v_mfma_f32_16x16x32_bf16 v[52:55], v[160:163], v[182:185], v[52:55]
	v_mfma_f32_16x16x32_bf16 v[48:51], v[174:177], v[182:185], v[48:51]
	v_mfma_f32_16x16x32_bf16 v[36:39], v[160:163], v[190:193], v[36:39]
	v_mfma_f32_16x16x32_bf16 v[32:35], v[174:177], v[190:193], v[32:35]
	v_mfma_f32_16x16x32_bf16 v[20:23], v[160:163], v[198:201], v[20:23]
	v_mfma_f32_16x16x32_bf16 v[16:19], v[174:177], v[198:201], v[16:19]
	v_mfma_f32_16x16x32_bf16 v[4:7], v[160:163], v[206:209], v[4:7]
	v_mfma_f32_16x16x32_bf16 v[0:3], v[174:177], v[206:209], v[0:3]
	v_mfma_f32_16x16x32_bf16 v[52:55], v[170:173], v[186:189], v[52:55]
	v_mfma_f32_16x16x32_bf16 v[48:51], v[178:181], v[186:189], v[48:51]
	v_mfma_f32_16x16x32_bf16 v[36:39], v[170:173], v[194:197], v[36:39]
	v_mfma_f32_16x16x32_bf16 v[32:35], v[178:181], v[194:197], v[32:35]
	v_mfma_f32_16x16x32_bf16 v[20:23], v[170:173], v[202:205], v[20:23]
	v_mfma_f32_16x16x32_bf16 v[16:19], v[178:181], v[202:205], v[16:19]
	v_mfma_f32_16x16x32_bf16 v[4:7], v[170:173], v[210:213], v[4:7]
	v_mfma_f32_16x16x32_bf16 v[0:3], v[178:181], v[210:213], v[0:3]
	s_setprio 0
	s_barrier
	s_cmp_gt_u32 s50, 41
	s_cbranch_scc0 .LBB0_1786
	s_and_b64 vcc, exec, s[8:9]
	s_cbranch_vccz .LBB0_1789
	s_barrier
